# v61 + GEMM K-loops: per-segment s_setprio toggling removed, one static s_setprio 1 at loop entry for the wave half that enters second (waves 4-7), reset at exit
# baseline (speedup 1.0000x reference)
; template <class Epi, class Sched, bool ALIGN_EPI = false, bool SP2 = false>
; __device__ __forceinline__ void gemm_phase(PG8_LAS unsigned char* lds, const Gemm g, const Sched& S, const Epi& E) {
;     ...
;         const bool has_next = S.next(ui + 1, nxt);
;         const char* nA = has_next ? (const char*)g.A + (size_t)nxt.pm * tstep : cA; const char* nB = has_next ? (const char*)g.Bt + (size_t)nxt.pn * tstep : cB;
;         for (int t = 0; t < nt; t += 2) {
;             const bool last = (t == nt - 2);
;             const char* a1 = cA + (size_t)(t + 1) * kstep;
;             const char* a2 = last ? nA : cA + (size_t)(t + 2) * kstep; const char* b2 = last ? nB : cB + (size_t)(t + 2) * kstep;
;             const char* a3 = a2 + kstep; const char* b3 = b2 + kstep;
;             if (last && has_next) S.a_ready(nxt);
.LBB0_184:
	s_ashr_i32 s23, s22, 31
	s_lshl_b64 s[24:25], s[22:23], 19
	s_add_u32 s24, s2, s24
	s_addc_u32 s25, s36, s25
	s_and_b64 s[26:27], s[8:9], exec
	s_cselect_b32 s23, s25, s29
	s_cselect_b32 s33, s24, s28
	s_ashr_i32 s21, s20, 31
	s_lshl_b64 s[26:27], s[20:21], 19
	s_add_u32 s26, s37, s26
	s_addc_u32 s27, s38, s27
	s_and_b64 s[34:35], s[8:9], exec
	s_cselect_b32 s21, s27, s31
	s_cselect_b32 s51, s26, s30
	s_add_u32 s28, s28, 0x40080
	s_addc_u32 s29, s29, 0
	s_add_u32 s52, s30, 0x100
	s_addc_u32 s53, s31, 0
	s_mov_b32 s54, -2
	s_cmp_eq_u64 s[16:17], 0
	s_cbranch_scc0 .Lmy_prio_185
	s_setprio 1

; #define PG8_STAGE(bufoff, gbase, voff) do { _Pragma("unroll") for (int _i = 0; _i < 2; ++_i) \
;         __builtin_amdgcn_global_load_lds((const unsigned*)((const char*)(gbase) + (voff)[_i]), (PG8_LAS unsigned*)(lds + (bufoff) + ldsw + _i * 8192), 16, 0, 0); } while (0)
; #define PG8_LDA(dst, b, h) do { _Pragma("unroll") for (int m = 0; m < 4; ++m) _Pragma("unroll") for (int k = 0; k < 2; ++k) dst[m][k] = *(const PG8_LAS bf16x8*)(lds + PG8_SA(b, h) + aoff + m * 2048 + k * 1024); } while (0)
; #define PG8_MMA(ai, bj, At, Bt) do { __builtin_amdgcn_s_setprio(1); _Pragma("unroll") for (int m = 0; m < 4; ++m) _Pragma("unroll") for (int n = 0; n < 2; ++n) _Pragma("unroll") for (int k = 0; k < 2; ++k) \
;         acc[ai][bj][m][n] = __builtin_amdgcn_mfma_f32_16x16x32_bf16(Bt[n][k], At[m][k], acc[ai][bj][m][n], 0, 0, 0); __builtin_amdgcn_s_setprio(0); } while (0)
; #define PG8_WAIT_V(n) asm volatile("s_waitcnt vmcnt(" #n ")" ::: "memory")
; #define PG8_WAIT_L(n) asm volatile("s_waitcnt lgkmcnt(" #n ")" ::: "memory")
; #define PG8_BAR __builtin_amdgcn_s_barrier()
; #define PG8_SCHED __builtin_amdgcn_sched_barrier(0)
; template <class Epi, class Sched, bool ALIGN_EPI = false, bool SP2 = false>
; __device__ __forceinline__ void gemm_phase(PG8_LAS unsigned char* lds, const Gemm g, const Sched& S, const Epi& E) {
;     ...
;             PG8_WAIT_V(8); PG8_WAIT_L(0); PG8_BAR; PG8_MMA(0, 0, At, B0); PG8_MMA(0, 1, At, B1); PG8_BAR; PG8_SCHED;
;             PG8_LDA(At, 0, 1); PG8_STAGE(PG8_SB(0, 0), b2, voffB); PG8_STAGE(PG8_SB(0, 1), b2 + hstep, voffB); PG8_STAGE(PG8_SA(0, 0), a2, voffA);
;             PG8_WAIT_V(8); PG8_WAIT_L(0); PG8_BAR; PG8_MMA(1, 0, At, B0); PG8_MMA(1, 1, At, B1); PG8_BAR; PG8_SCHED;
.Lodin_noz:
	s_waitcnt vmcnt(8)
	s_waitcnt lgkmcnt(0)
	s_barrier
	s_waitcnt lgkmcnt(0)
	v_mfma_f32_16x16x32_bf16 v[70:73], v[130:133], v[188:191], v[70:73]
	v_mfma_f32_16x16x32_bf16 v[66:69], v[158:161], v[188:191], v[66:69]
	v_mfma_f32_16x16x32_bf16 v[62:65], v[130:133], v[196:199], v[62:65]
	v_mfma_f32_16x16x32_bf16 v[58:61], v[158:161], v[196:199], v[58:61]
	v_mfma_f32_16x16x32_bf16 v[54:57], v[130:133], v[204:207], v[54:57]
	v_mfma_f32_16x16x32_bf16 v[50:53], v[158:161], v[204:207], v[50:53]
	v_mfma_f32_16x16x32_bf16 v[46:49], v[130:133], v[212:215], v[46:49]
	v_mfma_f32_16x16x32_bf16 v[42:45], v[158:161], v[212:215], v[42:45]
	v_mfma_f32_16x16x32_bf16 v[70:73], v[154:157], v[192:195], v[70:73]
	v_mfma_f32_16x16x32_bf16 v[66:69], v[162:165], v[192:195], v[66:69]
	v_mfma_f32_16x16x32_bf16 v[62:65], v[154:157], v[200:203], v[62:65]
	v_mfma_f32_16x16x32_bf16 v[58:61], v[162:165], v[200:203], v[58:61]
	v_mfma_f32_16x16x32_bf16 v[54:57], v[154:157], v[208:211], v[54:57]
	v_mfma_f32_16x16x32_bf16 v[50:53], v[162:165], v[208:211], v[50:53]
	v_mfma_f32_16x16x32_bf16 v[46:49], v[154:157], v[216:219], v[46:49]
	v_mfma_f32_16x16x32_bf16 v[42:45], v[162:165], v[216:219], v[42:45]
	v_mfma_f32_16x16x32_bf16 v[126:129], v[166:169], v[188:191], v[126:129]
	v_mfma_f32_16x16x32_bf16 v[122:125], v[180:183], v[188:191], v[122:125]
	v_mfma_f32_16x16x32_bf16 v[118:121], v[166:169], v[196:199], v[118:121]
	v_mfma_f32_16x16x32_bf16 v[114:117], v[180:183], v[196:199], v[114:117]
	v_mfma_f32_16x16x32_bf16 v[110:113], v[166:169], v[204:207], v[110:113]
	v_mfma_f32_16x16x32_bf16 v[106:109], v[180:183], v[204:207], v[106:109]
	v_mfma_f32_16x16x32_bf16 v[102:105], v[166:169], v[212:215], v[102:105]
	v_mfma_f32_16x16x32_bf16 v[98:101], v[180:183], v[212:215], v[98:101]
	v_mfma_f32_16x16x32_bf16 v[126:129], v[170:173], v[192:195], v[126:129]
	v_mfma_f32_16x16x32_bf16 v[122:125], v[184:187], v[192:195], v[122:125]
	v_mfma_f32_16x16x32_bf16 v[118:121], v[170:173], v[200:203], v[118:121]
	v_mfma_f32_16x16x32_bf16 v[114:117], v[184:187], v[200:203], v[114:117]
	v_mfma_f32_16x16x32_bf16 v[110:113], v[170:173], v[208:211], v[110:113]
	v_mfma_f32_16x16x32_bf16 v[106:109], v[184:187], v[208:211], v[106:109]
	v_mfma_f32_16x16x32_bf16 v[102:105], v[170:173], v[216:219], v[102:105]
	v_mfma_f32_16x16x32_bf16 v[98:101], v[184:187], v[216:219], v[98:101]
	s_barrier
	s_add_i32 s55, s55, s39
	v_lshl_add_u64 v[146:147], s[30:31], 0, v[138:139]
	s_mov_b32 m0, s55
	ds_read_b128 v[188:191], v153 offset:16384
	ds_read_b128 v[192:195], v153 offset:17408
	ds_read_b128 v[196:199], v153 offset:18432
	ds_read_b128 v[200:203], v153 offset:19456
	ds_read_b128 v[204:207], v153 offset:20480
	ds_read_b128 v[208:211], v153 offset:21504
	ds_read_b128 v[212:215], v153 offset:22528
	ds_read_b128 v[216:219], v153 offset:23552
	global_load_lds_dwordx4 v[146:147], off
	s_add_i32 m0, s55, 0x2000
	s_add_u32 s56, s30, 0x40000
	v_lshl_add_u64 v[220:221], s[30:31], 0, v[134:135]
	s_addc_u32 s57, s31, 0
	s_add_i32 s55, s58, s39
	global_load_lds_dwordx4 v[220:221], off
	v_lshl_add_u64 v[222:223], s[56:57], 0, v[138:139]
	s_mov_b32 m0, s55
	v_lshl_add_u64 v[228:229], s[34:35], 0, v[136:137]
	global_load_lds_dwordx4 v[222:223], off
	v_lshl_add_u64 v[222:223], s[56:57], 0, v[134:135]
	s_add_i32 m0, s55, 0x2000
	s_nop 0
	global_load_lds_dwordx4 v[222:223], off
	v_lshl_add_u64 v[222:223], s[34:35], 0, v[140:141]
	s_mov_b32 m0, s40
	s_nop 0
	global_load_lds_dwordx4 v[222:223], off
	s_mov_b32 m0, s41
	s_nop 0
	global_load_lds_dwordx4 v[228:229], off
	s_waitcnt vmcnt(8)
	s_waitcnt lgkmcnt(0)
	s_barrier
	s_waitcnt lgkmcnt(0)
	v_mfma_f32_16x16x32_bf16 v[30:33], v[130:133], v[188:191], v[30:33]
	v_mfma_f32_16x16x32_bf16 v[26:29], v[158:161], v[188:191], v[26:29]
	v_mfma_f32_16x16x32_bf16 v[22:25], v[130:133], v[196:199], v[22:25]
	v_mfma_f32_16x16x32_bf16 v[18:21], v[158:161], v[196:199], v[18:21]
	v_mfma_f32_16x16x32_bf16 v[14:17], v[130:133], v[204:207], v[14:17]
	v_mfma_f32_16x16x32_bf16 v[10:13], v[158:161], v[204:207], v[10:13]
	v_mfma_f32_16x16x32_bf16 v[6:9], v[130:133], v[212:215], v[6:9]
	v_mfma_f32_16x16x32_bf16 v[2:5], v[158:161], v[212:215], v[2:5]
	v_mfma_f32_16x16x32_bf16 v[30:33], v[154:157], v[192:195], v[30:33]
	v_mfma_f32_16x16x32_bf16 v[26:29], v[162:165], v[192:195], v[26:29]
	v_mfma_f32_16x16x32_bf16 v[22:25], v[154:157], v[200:203], v[22:25]
	v_mfma_f32_16x16x32_bf16 v[18:21], v[162:165], v[200:203], v[18:21]
	v_mfma_f32_16x16x32_bf16 v[14:17], v[154:157], v[208:211], v[14:17]
	v_mfma_f32_16x16x32_bf16 v[10:13], v[162:165], v[208:211], v[10:13]
	v_mfma_f32_16x16x32_bf16 v[6:9], v[154:157], v[216:219], v[6:9]
	v_mfma_f32_16x16x32_bf16 v[2:5], v[162:165], v[216:219], v[2:5]
	v_mfma_f32_16x16x32_bf16 v[94:97], v[166:169], v[188:191], v[94:97]
	v_mfma_f32_16x16x32_bf16 v[90:93], v[180:183], v[188:191], v[90:93]
	v_mfma_f32_16x16x32_bf16 v[86:89], v[166:169], v[196:199], v[86:89]
	v_mfma_f32_16x16x32_bf16 v[82:85], v[180:183], v[196:199], v[82:85]
	v_mfma_f32_16x16x32_bf16 v[78:81], v[166:169], v[204:207], v[78:81]
	v_mfma_f32_16x16x32_bf16 v[74:77], v[180:183], v[204:207], v[74:77]
	v_mfma_f32_16x16x32_bf16 v[38:41], v[166:169], v[212:215], v[38:41]
	v_mfma_f32_16x16x32_bf16 v[34:37], v[180:183], v[212:215], v[34:37]
	v_mfma_f32_16x16x32_bf16 v[94:97], v[170:173], v[192:195], v[94:97]
	v_mfma_f32_16x16x32_bf16 v[90:93], v[184:187], v[192:195], v[90:93]
	v_mfma_f32_16x16x32_bf16 v[86:89], v[170:173], v[200:203], v[86:89]
	v_mfma_f32_16x16x32_bf16 v[82:85], v[184:187], v[200:203], v[82:85]
	v_mfma_f32_16x16x32_bf16 v[78:81], v[170:173], v[208:211], v[78:81]
	v_mfma_f32_16x16x32_bf16 v[74:77], v[184:187], v[208:211], v[74:77]
	v_mfma_f32_16x16x32_bf16 v[38:41], v[170:173], v[216:219], v[38:41]
	v_mfma_f32_16x16x32_bf16 v[34:37], v[184:187], v[216:219], v[34:37]
	s_barrier
; #define PG8_STAGE(bufoff, gbase, voff) do { _Pragma("unroll") for (int _i = 0; _i < 2; ++_i) \
;         __builtin_amdgcn_global_load_lds((const unsigned*)((const char*)(gbase) + (voff)[_i]), (PG8_LAS unsigned*)(lds + (bufoff) + ldsw + _i * 8192), 16, 0, 0); } while (0)
; #define PG8_LDA(dst, b, h) do { _Pragma("unroll") for (int m = 0; m < 4; ++m) _Pragma("unroll") for (int k = 0; k < 2; ++k) dst[m][k] = *(const PG8_LAS bf16x8*)(lds + PG8_SA(b, h) + aoff + m * 2048 + k * 1024); } while (0)
; #define PG8_LDB(dst, b, h) do { _Pragma("unroll") for (int n = 0; n < 2; ++n) _Pragma("unroll") for (int k = 0; k < 2; ++k) dst[n][k] = *(const PG8_LAS bf16x8*)(lds + PG8_SB(b, h) + boff + n * 2048 + k * 1024); } while (0)
; #define PG8_MMA(ai, bj, At, Bt) do { __builtin_amdgcn_s_setprio(1); _Pragma("unroll") for (int m = 0; m < 4; ++m) _Pragma("unroll") for (int n = 0; n < 2; ++n) _Pragma("unroll") for (int k = 0; k < 2; ++k) \
;         acc[ai][bj][m][n] = __builtin_amdgcn_mfma_f32_16x16x32_bf16(Bt[n][k], At[m][k], acc[ai][bj][m][n], 0, 0, 0); __builtin_amdgcn_s_setprio(0); } while (0)
; #define PG8_WAIT_V(n) asm volatile("s_waitcnt vmcnt(" #n ")" ::: "memory")
; #define PG8_WAIT_L(n) asm volatile("s_waitcnt lgkmcnt(" #n ")" ::: "memory")
; #define PG8_BAR __builtin_amdgcn_s_barrier()
; #define PG8_SCHED __builtin_amdgcn_sched_barrier(0)
; template <class Epi, class Sched, bool ALIGN_EPI = false, bool SP2 = false>
; __device__ __forceinline__ void gemm_phase(PG8_LAS unsigned char* lds, const Gemm g, const Sched& S, const Epi& E) {
;     ...
;             PG8_LDB(B0, 1, 0); PG8_LDB(B1, 1, 1); PG8_SCHED; PG8_LDA(At, 1, 0); PG8_STAGE(PG8_SA(0, 1), a2 + hstep, voffA);
;             PG8_WAIT_V(8); PG8_WAIT_L(0); PG8_BAR; PG8_MMA(0, 0, At, B0); PG8_MMA(0, 1, At, B1); PG8_BAR; PG8_SCHED;
	s_add_i32 s55, 0, 0x18000
	v_add_u32_e32 v148, s55, v151
	s_add_i32 s56, 0, 0x1c000
	ds_read_b128 v[130:133], v148
	ds_read_b128 v[154:157], v148 offset:1024
	ds_read_b128 v[158:161], v148 offset:2048
	ds_read_b128 v[162:165], v148 offset:3072
	v_add_u32_e32 v148, s56, v151
	ds_read_b128 v[166:169], v148
	ds_read_b128 v[170:173], v148 offset:1024
	ds_read_b128 v[180:183], v148 offset:2048
	ds_read_b128 v[184:187], v148 offset:3072
	s_add_u32 s34, s34, 0x40000
	s_addc_u32 s35, s35, 0
	s_mov_b32 m0, s42
	v_lshl_add_u64 v[230:231], s[34:35], 0, v[140:141]
	ds_read_b128 v[188:191], v153 offset:32768
	ds_read_b128 v[192:195], v153 offset:33792
	ds_read_b128 v[196:199], v153 offset:34816
	ds_read_b128 v[200:203], v153 offset:35840
	ds_read_b128 v[204:207], v153 offset:36864
	ds_read_b128 v[208:211], v153 offset:37888
	ds_read_b128 v[212:215], v153 offset:38912
	ds_read_b128 v[216:219], v153 offset:39936
	global_load_lds_dwordx4 v[230:231], off
	v_lshl_add_u64 v[230:231], s[34:35], 0, v[136:137]
	s_mov_b32 m0, s43
	s_nop 0
	global_load_lds_dwordx4 v[230:231], off
	s_waitcnt vmcnt(8)
	s_waitcnt lgkmcnt(0)
	s_barrier
	s_waitcnt lgkmcnt(0)
	v_mfma_f32_16x16x32_bf16 v[70:73], v[130:133], v[188:191], v[70:73]
	v_mfma_f32_16x16x32_bf16 v[66:69], v[158:161], v[188:191], v[66:69]
	v_mfma_f32_16x16x32_bf16 v[62:65], v[130:133], v[196:199], v[62:65]
	v_mfma_f32_16x16x32_bf16 v[58:61], v[158:161], v[196:199], v[58:61]
	v_mfma_f32_16x16x32_bf16 v[54:57], v[130:133], v[204:207], v[54:57]
	v_mfma_f32_16x16x32_bf16 v[50:53], v[158:161], v[204:207], v[50:53]
	v_mfma_f32_16x16x32_bf16 v[46:49], v[130:133], v[212:215], v[46:49]
	v_mfma_f32_16x16x32_bf16 v[42:45], v[158:161], v[212:215], v[42:45]
	v_mfma_f32_16x16x32_bf16 v[70:73], v[154:157], v[192:195], v[70:73]
	v_mfma_f32_16x16x32_bf16 v[66:69], v[162:165], v[192:195], v[66:69]
	v_mfma_f32_16x16x32_bf16 v[62:65], v[154:157], v[200:203], v[62:65]
	v_mfma_f32_16x16x32_bf16 v[58:61], v[162:165], v[200:203], v[58:61]
	v_mfma_f32_16x16x32_bf16 v[54:57], v[154:157], v[208:211], v[54:57]
	v_mfma_f32_16x16x32_bf16 v[50:53], v[162:165], v[208:211], v[50:53]
	v_mfma_f32_16x16x32_bf16 v[46:49], v[154:157], v[216:219], v[46:49]
	v_mfma_f32_16x16x32_bf16 v[42:45], v[162:165], v[216:219], v[42:45]
	v_mfma_f32_16x16x32_bf16 v[126:129], v[166:169], v[188:191], v[126:129]
	v_mfma_f32_16x16x32_bf16 v[122:125], v[180:183], v[188:191], v[122:125]
	v_mfma_f32_16x16x32_bf16 v[118:121], v[166:169], v[196:199], v[118:121]
	v_mfma_f32_16x16x32_bf16 v[114:117], v[180:183], v[196:199], v[114:117]
	v_mfma_f32_16x16x32_bf16 v[110:113], v[166:169], v[204:207], v[110:113]
	v_mfma_f32_16x16x32_bf16 v[106:109], v[180:183], v[204:207], v[106:109]
	v_mfma_f32_16x16x32_bf16 v[102:105], v[166:169], v[212:215], v[102:105]
	v_mfma_f32_16x16x32_bf16 v[98:101], v[180:183], v[212:215], v[98:101]
	v_mfma_f32_16x16x32_bf16 v[126:129], v[170:173], v[192:195], v[126:129]
	v_mfma_f32_16x16x32_bf16 v[122:125], v[184:187], v[192:195], v[122:125]
	v_mfma_f32_16x16x32_bf16 v[118:121], v[170:173], v[200:203], v[118:121]
	v_mfma_f32_16x16x32_bf16 v[114:117], v[184:187], v[200:203], v[114:117]
	v_mfma_f32_16x16x32_bf16 v[110:113], v[170:173], v[208:211], v[110:113]
	v_mfma_f32_16x16x32_bf16 v[106:109], v[184:187], v[208:211], v[106:109]
	v_mfma_f32_16x16x32_bf16 v[102:105], v[170:173], v[216:219], v[102:105]
	v_mfma_f32_16x16x32_bf16 v[98:101], v[184:187], v[216:219], v[98:101]
	s_barrier
; #define PG8_STAGE(bufoff, gbase, voff) do { _Pragma("unroll") for (int _i = 0; _i < 2; ++_i) \
;         __builtin_amdgcn_global_load_lds((const unsigned*)((const char*)(gbase) + (voff)[_i]), (PG8_LAS unsigned*)(lds + (bufoff) + ldsw + _i * 8192), 16, 0, 0); } while (0)
; #define PG8_LDA(dst, b, h) do { _Pragma("unroll") for (int m = 0; m < 4; ++m) _Pragma("unroll") for (int k = 0; k < 2; ++k) dst[m][k] = *(const PG8_LAS bf16x8*)(lds + PG8_SA(b, h) + aoff + m * 2048 + k * 1024); } while (0)
; #define PG8_MMA(ai, bj, At, Bt) do { __builtin_amdgcn_s_setprio(1); _Pragma("unroll") for (int m = 0; m < 4; ++m) _Pragma("unroll") for (int n = 0; n < 2; ++n) _Pragma("unroll") for (int k = 0; k < 2; ++k) \
;         acc[ai][bj][m][n] = __builtin_amdgcn_mfma_f32_16x16x32_bf16(Bt[n][k], At[m][k], acc[ai][bj][m][n], 0, 0, 0); __builtin_amdgcn_s_setprio(0); } while (0)
; #define PG8_WAIT_V(n) asm volatile("s_waitcnt vmcnt(" #n ")" ::: "memory")
; #define PG8_WAIT_L(n) asm volatile("s_waitcnt lgkmcnt(" #n ")" ::: "memory")
; #define PG8_BAR __builtin_amdgcn_s_barrier()
; #define PG8_SCHED __builtin_amdgcn_sched_barrier(0)
; template <class Epi, class Sched, bool ALIGN_EPI = false, bool SP2 = false>
; __device__ __forceinline__ void gemm_phase(PG8_LAS unsigned char* lds, const Gemm g, const Sched& S, const Epi& E) {
;     ...
;             PG8_LDA(At, 1, 1); PG8_STAGE(PG8_SB(1, 0), b3, voffB); PG8_STAGE(PG8_SB(1, 1), b3 + hstep, voffB); PG8_STAGE(PG8_SA(1, 0), a3, voffA);
;             PG8_WAIT_V(8); PG8_WAIT_L(0); PG8_BAR; PG8_MMA(1, 0, At, B0); PG8_MMA(1, 1, At, B1); PG8_BAR; PG8_SCHED;
;     ...
;         if constexpr (ALIGN_EPI) { if (wr == 0) PG8_BAR; }
	s_add_i32 s34, s55, s39
	v_lshl_add_u64 v[146:147], v[146:147], 0, s[96:97]
	s_mov_b32 m0, s34
	ds_read_b128 v[188:191], v153 offset:49152
	ds_read_b128 v[192:195], v153 offset:50176
	ds_read_b128 v[196:199], v153 offset:51200
	ds_read_b128 v[200:203], v153 offset:52224
	ds_read_b128 v[204:207], v153 offset:53248
	ds_read_b128 v[208:211], v153 offset:54272
	ds_read_b128 v[212:215], v153 offset:55296
	ds_read_b128 v[216:219], v153 offset:56320
	global_load_lds_dwordx4 v[146:147], off
	s_add_i32 m0, s34, 0x2000
	s_add_u32 s30, s30, 0x40080
	v_lshl_add_u64 v[146:147], v[220:221], 0, s[96:97]
	s_addc_u32 s31, s31, 0
	s_add_i32 s34, s56, s39
	global_load_lds_dwordx4 v[146:147], off
	v_lshl_add_u64 v[146:147], s[30:31], 0, v[138:139]
	s_mov_b32 m0, s34
	s_nop 0
	global_load_lds_dwordx4 v[146:147], off
	v_lshl_add_u64 v[146:147], s[30:31], 0, v[134:135]
	s_add_i32 m0, s34, 0x2000
	s_nop 0
	global_load_lds_dwordx4 v[146:147], off
	v_lshl_add_u64 v[146:147], v[222:223], 0, s[96:97]
	s_mov_b32 m0, s48
	s_nop 0
	global_load_lds_dwordx4 v[146:147], off
	v_lshl_add_u64 v[146:147], v[228:229], 0, s[96:97]
	s_mov_b32 m0, s49
	s_nop 0
	global_load_lds_dwordx4 v[146:147], off
	s_waitcnt vmcnt(8)
	s_waitcnt lgkmcnt(0)
	s_barrier
	s_waitcnt lgkmcnt(0)
	v_mfma_f32_16x16x32_bf16 v[30:33], v[130:133], v[188:191], v[30:33]
	v_mfma_f32_16x16x32_bf16 v[26:29], v[158:161], v[188:191], v[26:29]
	v_mfma_f32_16x16x32_bf16 v[22:25], v[130:133], v[196:199], v[22:25]
	v_mfma_f32_16x16x32_bf16 v[18:21], v[158:161], v[196:199], v[18:21]
	v_mfma_f32_16x16x32_bf16 v[14:17], v[130:133], v[204:207], v[14:17]
	v_mfma_f32_16x16x32_bf16 v[10:13], v[158:161], v[204:207], v[10:13]
	v_mfma_f32_16x16x32_bf16 v[6:9], v[130:133], v[212:215], v[6:9]
	v_mfma_f32_16x16x32_bf16 v[2:5], v[158:161], v[212:215], v[2:5]
	v_mfma_f32_16x16x32_bf16 v[30:33], v[154:157], v[192:195], v[30:33]
	v_mfma_f32_16x16x32_bf16 v[26:29], v[162:165], v[192:195], v[26:29]
	v_mfma_f32_16x16x32_bf16 v[22:25], v[154:157], v[200:203], v[22:25]
	v_mfma_f32_16x16x32_bf16 v[18:21], v[162:165], v[200:203], v[18:21]
	v_mfma_f32_16x16x32_bf16 v[14:17], v[154:157], v[208:211], v[14:17]
	v_mfma_f32_16x16x32_bf16 v[10:13], v[162:165], v[208:211], v[10:13]
	v_mfma_f32_16x16x32_bf16 v[6:9], v[154:157], v[216:219], v[6:9]
	v_mfma_f32_16x16x32_bf16 v[2:5], v[162:165], v[216:219], v[2:5]
	v_mfma_f32_16x16x32_bf16 v[94:97], v[166:169], v[188:191], v[94:97]
	v_mfma_f32_16x16x32_bf16 v[90:93], v[180:183], v[188:191], v[90:93]
	v_mfma_f32_16x16x32_bf16 v[86:89], v[166:169], v[196:199], v[86:89]
	v_mfma_f32_16x16x32_bf16 v[82:85], v[180:183], v[196:199], v[82:85]
	v_mfma_f32_16x16x32_bf16 v[78:81], v[166:169], v[204:207], v[78:81]
	v_mfma_f32_16x16x32_bf16 v[74:77], v[180:183], v[204:207], v[74:77]
	v_mfma_f32_16x16x32_bf16 v[38:41], v[166:169], v[212:215], v[38:41]
	v_mfma_f32_16x16x32_bf16 v[34:37], v[180:183], v[212:215], v[34:37]
	v_mfma_f32_16x16x32_bf16 v[94:97], v[170:173], v[192:195], v[94:97]
	v_mfma_f32_16x16x32_bf16 v[90:93], v[184:187], v[192:195], v[90:93]
	v_mfma_f32_16x16x32_bf16 v[86:89], v[170:173], v[200:203], v[86:89]
	v_mfma_f32_16x16x32_bf16 v[82:85], v[184:187], v[200:203], v[82:85]
	v_mfma_f32_16x16x32_bf16 v[78:81], v[170:173], v[208:211], v[78:81]
	v_mfma_f32_16x16x32_bf16 v[74:77], v[184:187], v[208:211], v[74:77]
	v_mfma_f32_16x16x32_bf16 v[38:41], v[170:173], v[216:219], v[38:41]
	v_mfma_f32_16x16x32_bf16 v[34:37], v[184:187], v[216:219], v[34:37]
	s_barrier
	s_add_i32 s54, s54, 2
	s_add_u32 s28, s28, 0x100
	s_addc_u32 s29, s29, 0
	s_add_u32 s52, s52, 0x100
	s_addc_u32 s53, s53, 0
	s_cmp_gt_u32 s54, 13
	s_cbranch_scc0 .LBB0_185
	s_setprio 0
	s_and_b64 vcc, exec, s[16:17]
	s_cbranch_vccz .LBB0_188
	s_barrier

; template <class Epi, class Sched, bool ALIGN_EPI = false, bool SP2 = false>
; __device__ __forceinline__ void gemm_phase(PG8_LAS unsigned char* lds, const Gemm g, const Sched& S, const Epi& E) {
;     ...
;         const bool has_next = S.next(ui + 1, nxt);
;         const char* nA = has_next ? (const char*)g.A + (size_t)nxt.pm * tstep : cA; const char* nB = has_next ? (const char*)g.Bt + (size_t)nxt.pn * tstep : cB;
;         for (int t = 0; t < nt; t += 2) {
;             const bool last = (t == nt - 2);
;             const char* a1 = cA + (size_t)(t + 1) * kstep;
;             const char* a2 = last ? nA : cA + (size_t)(t + 2) * kstep; const char* b2 = last ? nB : cB + (size_t)(t + 2) * kstep;
;             const char* a3 = a2 + kstep; const char* b3 = b2 + kstep;
;             if (last && has_next) S.a_ready(nxt);
.LBB0_632:
	s_ashr_i32 s29, s28, 31
	s_lshl_b64 s[30:31], s[28:29], 19
	s_add_u32 s30, s38, s30
	s_addc_u32 s31, s39, s31
	s_and_b64 s[34:35], s[8:9], exec
	s_cselect_b32 s5, s31, s11
	s_cselect_b32 s25, s30, s10
	s_ashr_i32 s27, s26, 31
	s_lshl_b64 s[34:35], s[26:27], 19
	s_add_u32 s34, s40, s34
	s_addc_u32 s35, s41, s35
	s_and_b64 s[36:37], s[8:9], exec
	s_cselect_b32 s27, s35, s13
	s_cselect_b32 s29, s34, s12
	s_add_u32 s10, s10, 0x40080
	s_addc_u32 s11, s11, 0
	s_add_u32 s33, s12, 0x100
	s_addc_u32 s54, s13, 0
	s_mov_b32 s55, -2
	s_waitcnt lgkmcnt(0)
	s_cmp_eq_u64 s[20:21], 0
	s_cbranch_scc0 .Lmy_prio_633
	s_setprio 1

; #define PG8_STAGE(bufoff, gbase, voff) do { _Pragma("unroll") for (int _i = 0; _i < 2; ++_i) \
;         __builtin_amdgcn_global_load_lds((const unsigned*)((const char*)(gbase) + (voff)[_i]), (PG8_LAS unsigned*)(lds + (bufoff) + ldsw + _i * 8192), 16, 0, 0); } while (0)
; #define PG8_LDA(dst, b, h) do { _Pragma("unroll") for (int m = 0; m < 4; ++m) _Pragma("unroll") for (int k = 0; k < 2; ++k) dst[m][k] = *(const PG8_LAS bf16x8*)(lds + PG8_SA(b, h) + aoff + m * 2048 + k * 1024); } while (0)
; #define PG8_MMA(ai, bj, At, Bt) do { __builtin_amdgcn_s_setprio(1); _Pragma("unroll") for (int m = 0; m < 4; ++m) _Pragma("unroll") for (int n = 0; n < 2; ++n) _Pragma("unroll") for (int k = 0; k < 2; ++k) \
;         acc[ai][bj][m][n] = __builtin_amdgcn_mfma_f32_16x16x32_bf16(Bt[n][k], At[m][k], acc[ai][bj][m][n], 0, 0, 0); __builtin_amdgcn_s_setprio(0); } while (0)
; #define PG8_WAIT_V(n) asm volatile("s_waitcnt vmcnt(" #n ")" ::: "memory")
; #define PG8_WAIT_L(n) asm volatile("s_waitcnt lgkmcnt(" #n ")" ::: "memory")
; #define PG8_BAR __builtin_amdgcn_s_barrier()
; #define PG8_SCHED __builtin_amdgcn_sched_barrier(0)
; template <class Epi, class Sched, bool ALIGN_EPI = false, bool SP2 = false>
; __device__ __forceinline__ void gemm_phase(PG8_LAS unsigned char* lds, const Gemm g, const Sched& S, const Epi& E) {
;     ...
;             PG8_WAIT_V(8); PG8_WAIT_L(0); PG8_BAR; PG8_MMA(0, 0, At, B0); PG8_MMA(0, 1, At, B1); PG8_BAR; PG8_SCHED;
;             PG8_LDA(At, 0, 1); PG8_STAGE(PG8_SB(0, 0), b2, voffB); PG8_STAGE(PG8_SB(0, 1), b2 + hstep, voffB); PG8_STAGE(PG8_SA(0, 0), a2, voffA);
;             PG8_WAIT_V(8); PG8_WAIT_L(0); PG8_BAR; PG8_MMA(1, 0, At, B0); PG8_MMA(1, 1, At, B1); PG8_BAR; PG8_SCHED;
.Lodout_noz:
	s_waitcnt vmcnt(8)
	s_waitcnt lgkmcnt(0)
	s_barrier
	s_waitcnt lgkmcnt(0)
	v_mfma_f32_16x16x32_bf16 v[158:161], v[66:69], v[162:165], v[158:161]
	v_mfma_f32_16x16x32_bf16 v[154:157], v[82:85], v[162:165], v[154:157]
	v_mfma_f32_16x16x32_bf16 v[142:145], v[66:69], v[188:191], v[142:145]
	v_mfma_f32_16x16x32_bf16 v[138:141], v[82:85], v[188:191], v[138:141]
	v_mfma_f32_16x16x32_bf16 v[114:117], v[66:69], v[196:199], v[114:117]
	v_mfma_f32_16x16x32_bf16 v[110:113], v[82:85], v[196:199], v[110:113]
	v_mfma_f32_16x16x32_bf16 v[90:93], v[66:69], v[210:213], v[90:93]
	v_mfma_f32_16x16x32_bf16 v[86:89], v[82:85], v[210:213], v[86:89]
	v_mfma_f32_16x16x32_bf16 v[158:161], v[70:73], v[166:169], v[158:161]
	v_mfma_f32_16x16x32_bf16 v[154:157], v[94:97], v[166:169], v[154:157]
	v_mfma_f32_16x16x32_bf16 v[142:145], v[70:73], v[192:195], v[142:145]
	v_mfma_f32_16x16x32_bf16 v[138:141], v[94:97], v[192:195], v[138:141]
	v_mfma_f32_16x16x32_bf16 v[114:117], v[70:73], v[206:209], v[114:117]
	v_mfma_f32_16x16x32_bf16 v[110:113], v[94:97], v[206:209], v[110:113]
	v_mfma_f32_16x16x32_bf16 v[90:93], v[70:73], v[214:217], v[90:93]
	v_mfma_f32_16x16x32_bf16 v[86:89], v[94:97], v[214:217], v[86:89]
	v_mfma_f32_16x16x32_bf16 v[150:153], v[106:109], v[162:165], v[150:153]
	v_mfma_f32_16x16x32_bf16 v[146:149], v[130:133], v[162:165], v[146:149]
	v_mfma_f32_16x16x32_bf16 v[126:129], v[106:109], v[188:191], v[126:129]
	v_mfma_f32_16x16x32_bf16 v[122:125], v[130:133], v[188:191], v[122:125]
	v_mfma_f32_16x16x32_bf16 v[102:105], v[106:109], v[196:199], v[102:105]
	v_mfma_f32_16x16x32_bf16 v[98:101], v[130:133], v[196:199], v[98:101]
	v_mfma_f32_16x16x32_bf16 v[78:81], v[106:109], v[210:213], v[78:81]
	v_mfma_f32_16x16x32_bf16 v[74:77], v[130:133], v[210:213], v[74:77]
	v_mfma_f32_16x16x32_bf16 v[150:153], v[118:121], v[166:169], v[150:153]
	v_mfma_f32_16x16x32_bf16 v[146:149], v[134:137], v[166:169], v[146:149]
	v_mfma_f32_16x16x32_bf16 v[126:129], v[118:121], v[192:195], v[126:129]
	v_mfma_f32_16x16x32_bf16 v[122:125], v[134:137], v[192:195], v[122:125]
	v_mfma_f32_16x16x32_bf16 v[102:105], v[118:121], v[206:209], v[102:105]
	v_mfma_f32_16x16x32_bf16 v[98:101], v[134:137], v[206:209], v[98:101]
	v_mfma_f32_16x16x32_bf16 v[78:81], v[118:121], v[214:217], v[78:81]
	v_mfma_f32_16x16x32_bf16 v[74:77], v[134:137], v[214:217], v[74:77]
	s_barrier
	s_add_i32 s56, s56, s42
	v_lshl_add_u64 v[200:201], s[12:13], 0, v[180:181]
	s_mov_b32 m0, s56
	ds_read_b128 v[162:165], v204 offset:16384
	ds_read_b128 v[166:169], v204 offset:17408
	ds_read_b128 v[188:191], v204 offset:18432
	ds_read_b128 v[192:195], v204 offset:19456
	ds_read_b128 v[196:199], v204 offset:20480
	ds_read_b128 v[206:209], v204 offset:21504
	ds_read_b128 v[210:213], v204 offset:22528
	ds_read_b128 v[214:217], v204 offset:23552
	global_load_lds_dwordx4 v[200:201], off
	s_add_i32 m0, s56, 0x2000
	s_add_u32 s56, s12, 0x40000
	v_lshl_add_u64 v[218:219], s[12:13], 0, v[170:171]
	s_addc_u32 s57, s13, 0
	s_add_i32 s58, s58, s42
	global_load_lds_dwordx4 v[218:219], off
	v_lshl_add_u64 v[220:221], s[56:57], 0, v[180:181]
	s_mov_b32 m0, s58
	v_lshl_add_u64 v[222:223], s[36:37], 0, v[172:173]
	global_load_lds_dwordx4 v[220:221], off
	v_lshl_add_u64 v[220:221], s[56:57], 0, v[170:171]
	s_add_i32 m0, s58, 0x2000
	s_nop 0
	global_load_lds_dwordx4 v[220:221], off
	v_lshl_add_u64 v[220:221], s[36:37], 0, v[182:183]
	s_mov_b32 m0, s43
	s_nop 0
	global_load_lds_dwordx4 v[220:221], off
	s_mov_b32 m0, s44
	s_nop 0
	global_load_lds_dwordx4 v[222:223], off
	s_waitcnt vmcnt(8)
	s_waitcnt lgkmcnt(0)
	s_barrier
	s_waitcnt lgkmcnt(0)
	v_mfma_f32_16x16x32_bf16 v[62:65], v[66:69], v[162:165], v[62:65]
	v_mfma_f32_16x16x32_bf16 v[58:61], v[82:85], v[162:165], v[58:61]
	v_mfma_f32_16x16x32_bf16 v[46:49], v[66:69], v[188:191], v[46:49]
	v_mfma_f32_16x16x32_bf16 v[42:45], v[82:85], v[188:191], v[42:45]
	v_mfma_f32_16x16x32_bf16 v[30:33], v[66:69], v[196:199], v[30:33]
	v_mfma_f32_16x16x32_bf16 v[26:29], v[82:85], v[196:199], v[26:29]
	v_mfma_f32_16x16x32_bf16 v[14:17], v[66:69], v[210:213], v[14:17]
	v_mfma_f32_16x16x32_bf16 v[10:13], v[82:85], v[210:213], v[10:13]
	v_mfma_f32_16x16x32_bf16 v[62:65], v[70:73], v[166:169], v[62:65]
	v_mfma_f32_16x16x32_bf16 v[58:61], v[94:97], v[166:169], v[58:61]
	v_mfma_f32_16x16x32_bf16 v[46:49], v[70:73], v[192:195], v[46:49]
	v_mfma_f32_16x16x32_bf16 v[42:45], v[94:97], v[192:195], v[42:45]
	v_mfma_f32_16x16x32_bf16 v[30:33], v[70:73], v[206:209], v[30:33]
	v_mfma_f32_16x16x32_bf16 v[26:29], v[94:97], v[206:209], v[26:29]
	v_mfma_f32_16x16x32_bf16 v[14:17], v[70:73], v[214:217], v[14:17]
	v_mfma_f32_16x16x32_bf16 v[10:13], v[94:97], v[214:217], v[10:13]
	v_mfma_f32_16x16x32_bf16 v[54:57], v[106:109], v[162:165], v[54:57]
	v_mfma_f32_16x16x32_bf16 v[50:53], v[130:133], v[162:165], v[50:53]
	v_mfma_f32_16x16x32_bf16 v[38:41], v[106:109], v[188:191], v[38:41]
	v_mfma_f32_16x16x32_bf16 v[34:37], v[130:133], v[188:191], v[34:37]
	v_mfma_f32_16x16x32_bf16 v[22:25], v[106:109], v[196:199], v[22:25]
	v_mfma_f32_16x16x32_bf16 v[18:21], v[130:133], v[196:199], v[18:21]
	v_mfma_f32_16x16x32_bf16 v[6:9], v[106:109], v[210:213], v[6:9]
	v_mfma_f32_16x16x32_bf16 v[2:5], v[130:133], v[210:213], v[2:5]
	v_mfma_f32_16x16x32_bf16 v[54:57], v[118:121], v[166:169], v[54:57]
	v_mfma_f32_16x16x32_bf16 v[50:53], v[134:137], v[166:169], v[50:53]
	v_mfma_f32_16x16x32_bf16 v[38:41], v[118:121], v[192:195], v[38:41]
	v_mfma_f32_16x16x32_bf16 v[34:37], v[134:137], v[192:195], v[34:37]
	v_mfma_f32_16x16x32_bf16 v[22:25], v[118:121], v[206:209], v[22:25]
	v_mfma_f32_16x16x32_bf16 v[18:21], v[134:137], v[206:209], v[18:21]
	v_mfma_f32_16x16x32_bf16 v[6:9], v[118:121], v[214:217], v[6:9]
	v_mfma_f32_16x16x32_bf16 v[2:5], v[134:137], v[214:217], v[2:5]
	s_barrier
; #define PG8_STAGE(bufoff, gbase, voff) do { _Pragma("unroll") for (int _i = 0; _i < 2; ++_i) \
;         __builtin_amdgcn_global_load_lds((const unsigned*)((const char*)(gbase) + (voff)[_i]), (PG8_LAS unsigned*)(lds + (bufoff) + ldsw + _i * 8192), 16, 0, 0); } while (0)
; #define PG8_LDA(dst, b, h) do { _Pragma("unroll") for (int m = 0; m < 4; ++m) _Pragma("unroll") for (int k = 0; k < 2; ++k) dst[m][k] = *(const PG8_LAS bf16x8*)(lds + PG8_SA(b, h) + aoff + m * 2048 + k * 1024); } while (0)
; #define PG8_LDB(dst, b, h) do { _Pragma("unroll") for (int n = 0; n < 2; ++n) _Pragma("unroll") for (int k = 0; k < 2; ++k) dst[n][k] = *(const PG8_LAS bf16x8*)(lds + PG8_SB(b, h) + boff + n * 2048 + k * 1024); } while (0)
; #define PG8_MMA(ai, bj, At, Bt) do { __builtin_amdgcn_s_setprio(1); _Pragma("unroll") for (int m = 0; m < 4; ++m) _Pragma("unroll") for (int n = 0; n < 2; ++n) _Pragma("unroll") for (int k = 0; k < 2; ++k) \
;         acc[ai][bj][m][n] = __builtin_amdgcn_mfma_f32_16x16x32_bf16(Bt[n][k], At[m][k], acc[ai][bj][m][n], 0, 0, 0); __builtin_amdgcn_s_setprio(0); } while (0)
; #define PG8_WAIT_V(n) asm volatile("s_waitcnt vmcnt(" #n ")" ::: "memory")
; #define PG8_WAIT_L(n) asm volatile("s_waitcnt lgkmcnt(" #n ")" ::: "memory")
; #define PG8_BAR __builtin_amdgcn_s_barrier()
; #define PG8_SCHED __builtin_amdgcn_sched_barrier(0)
; template <class Epi, class Sched, bool ALIGN_EPI = false, bool SP2 = false>
; __device__ __forceinline__ void gemm_phase(PG8_LAS unsigned char* lds, const Gemm g, const Sched& S, const Epi& E) {
;     ...
;             PG8_LDB(B0, 1, 0); PG8_LDB(B1, 1, 1); PG8_SCHED; PG8_LDA(At, 1, 0); PG8_STAGE(PG8_SA(0, 1), a2 + hstep, voffA);
;             PG8_WAIT_V(8); PG8_WAIT_L(0); PG8_BAR; PG8_MMA(0, 0, At, B0); PG8_MMA(0, 1, At, B1); PG8_BAR; PG8_SCHED;
	s_add_i32 s56, 0, 0x18000
	s_add_i32 s57, 0, 0x1c000
	v_add_u32_e32 v94, s56, v203
	v_add_u32_e32 v134, s57, v203
	ds_read_b128 v[66:69], v94
	ds_read_b128 v[70:73], v94 offset:1024
	ds_read_b128 v[82:85], v94 offset:2048
	ds_read_b128 v[94:97], v94 offset:3072
	ds_read_b128 v[106:109], v134
	ds_read_b128 v[118:121], v134 offset:1024
	ds_read_b128 v[130:133], v134 offset:2048
	ds_read_b128 v[134:137], v134 offset:3072
	s_add_u32 s36, s36, 0x40000
	s_addc_u32 s37, s37, 0
	s_mov_b32 m0, s45
	v_lshl_add_u64 v[228:229], s[36:37], 0, v[182:183]
	ds_read_b128 v[162:165], v204 offset:32768
	ds_read_b128 v[166:169], v204 offset:33792
	ds_read_b128 v[188:191], v204 offset:34816
	ds_read_b128 v[192:195], v204 offset:35840
	ds_read_b128 v[196:199], v204 offset:36864
	ds_read_b128 v[206:209], v204 offset:37888
	ds_read_b128 v[210:213], v204 offset:38912
	ds_read_b128 v[214:217], v204 offset:39936
	global_load_lds_dwordx4 v[228:229], off
	v_lshl_add_u64 v[228:229], s[36:37], 0, v[172:173]
	s_mov_b32 m0, s46
	s_nop 0
	global_load_lds_dwordx4 v[228:229], off
	s_waitcnt vmcnt(8)
	s_waitcnt lgkmcnt(0)
	s_barrier
	s_waitcnt lgkmcnt(0)
	v_mfma_f32_16x16x32_bf16 v[158:161], v[66:69], v[162:165], v[158:161]
	v_mfma_f32_16x16x32_bf16 v[154:157], v[82:85], v[162:165], v[154:157]
	v_mfma_f32_16x16x32_bf16 v[142:145], v[66:69], v[188:191], v[142:145]
	v_mfma_f32_16x16x32_bf16 v[138:141], v[82:85], v[188:191], v[138:141]
	v_mfma_f32_16x16x32_bf16 v[114:117], v[66:69], v[196:199], v[114:117]
	v_mfma_f32_16x16x32_bf16 v[110:113], v[82:85], v[196:199], v[110:113]
	v_mfma_f32_16x16x32_bf16 v[90:93], v[66:69], v[210:213], v[90:93]
	v_mfma_f32_16x16x32_bf16 v[86:89], v[82:85], v[210:213], v[86:89]
	v_mfma_f32_16x16x32_bf16 v[158:161], v[70:73], v[166:169], v[158:161]
	v_mfma_f32_16x16x32_bf16 v[154:157], v[94:97], v[166:169], v[154:157]
	v_mfma_f32_16x16x32_bf16 v[142:145], v[70:73], v[192:195], v[142:145]
	v_mfma_f32_16x16x32_bf16 v[138:141], v[94:97], v[192:195], v[138:141]
	v_mfma_f32_16x16x32_bf16 v[114:117], v[70:73], v[206:209], v[114:117]
	v_mfma_f32_16x16x32_bf16 v[110:113], v[94:97], v[206:209], v[110:113]
	v_mfma_f32_16x16x32_bf16 v[90:93], v[70:73], v[214:217], v[90:93]
	v_mfma_f32_16x16x32_bf16 v[86:89], v[94:97], v[214:217], v[86:89]
	v_mfma_f32_16x16x32_bf16 v[150:153], v[106:109], v[162:165], v[150:153]
	v_mfma_f32_16x16x32_bf16 v[146:149], v[130:133], v[162:165], v[146:149]
	v_mfma_f32_16x16x32_bf16 v[126:129], v[106:109], v[188:191], v[126:129]
	v_mfma_f32_16x16x32_bf16 v[122:125], v[130:133], v[188:191], v[122:125]
	v_mfma_f32_16x16x32_bf16 v[102:105], v[106:109], v[196:199], v[102:105]
	v_mfma_f32_16x16x32_bf16 v[98:101], v[130:133], v[196:199], v[98:101]
	v_mfma_f32_16x16x32_bf16 v[78:81], v[106:109], v[210:213], v[78:81]
	v_mfma_f32_16x16x32_bf16 v[74:77], v[130:133], v[210:213], v[74:77]
	v_mfma_f32_16x16x32_bf16 v[150:153], v[118:121], v[166:169], v[150:153]
	v_mfma_f32_16x16x32_bf16 v[146:149], v[134:137], v[166:169], v[146:149]
	v_mfma_f32_16x16x32_bf16 v[126:129], v[118:121], v[192:195], v[126:129]
	v_mfma_f32_16x16x32_bf16 v[122:125], v[134:137], v[192:195], v[122:125]
	v_mfma_f32_16x16x32_bf16 v[102:105], v[118:121], v[206:209], v[102:105]
	v_mfma_f32_16x16x32_bf16 v[98:101], v[134:137], v[206:209], v[98:101]
	v_mfma_f32_16x16x32_bf16 v[78:81], v[118:121], v[214:217], v[78:81]
	v_mfma_f32_16x16x32_bf16 v[74:77], v[134:137], v[214:217], v[74:77]
	s_barrier
; #define PG8_STAGE(bufoff, gbase, voff) do { _Pragma("unroll") for (int _i = 0; _i < 2; ++_i) \
;         __builtin_amdgcn_global_load_lds((const unsigned*)((const char*)(gbase) + (voff)[_i]), (PG8_LAS unsigned*)(lds + (bufoff) + ldsw + _i * 8192), 16, 0, 0); } while (0)
; #define PG8_LDA(dst, b, h) do { _Pragma("unroll") for (int m = 0; m < 4; ++m) _Pragma("unroll") for (int k = 0; k < 2; ++k) dst[m][k] = *(const PG8_LAS bf16x8*)(lds + PG8_SA(b, h) + aoff + m * 2048 + k * 1024); } while (0)
; #define PG8_MMA(ai, bj, At, Bt) do { __builtin_amdgcn_s_setprio(1); _Pragma("unroll") for (int m = 0; m < 4; ++m) _Pragma("unroll") for (int n = 0; n < 2; ++n) _Pragma("unroll") for (int k = 0; k < 2; ++k) \
;         acc[ai][bj][m][n] = __builtin_amdgcn_mfma_f32_16x16x32_bf16(Bt[n][k], At[m][k], acc[ai][bj][m][n], 0, 0, 0); __builtin_amdgcn_s_setprio(0); } while (0)
; #define PG8_WAIT_V(n) asm volatile("s_waitcnt vmcnt(" #n ")" ::: "memory")
; #define PG8_WAIT_L(n) asm volatile("s_waitcnt lgkmcnt(" #n ")" ::: "memory")
; #define PG8_BAR __builtin_amdgcn_s_barrier()
; #define PG8_SCHED __builtin_amdgcn_sched_barrier(0)
; template <class Epi, class Sched, bool ALIGN_EPI = false, bool SP2 = false>
; __device__ __forceinline__ void gemm_phase(PG8_LAS unsigned char* lds, const Gemm g, const Sched& S, const Epi& E) {
;     ...
;             PG8_LDA(At, 1, 1); PG8_STAGE(PG8_SB(1, 0), b3, voffB); PG8_STAGE(PG8_SB(1, 1), b3 + hstep, voffB); PG8_STAGE(PG8_SA(1, 0), a3, voffA);
;             PG8_WAIT_V(8); PG8_WAIT_L(0); PG8_BAR; PG8_MMA(1, 0, At, B0); PG8_MMA(1, 1, At, B1); PG8_BAR; PG8_SCHED;
;     ...
;         if constexpr (ALIGN_EPI) { if (wr == 0) PG8_BAR; }
	s_add_i32 s36, s56, s42
	v_lshl_add_u64 v[200:201], v[200:201], 0, s[96:97]
	s_mov_b32 m0, s36
	ds_read_b128 v[162:165], v204 offset:49152
	ds_read_b128 v[166:169], v204 offset:50176
	ds_read_b128 v[188:191], v204 offset:51200
	ds_read_b128 v[192:195], v204 offset:52224
	ds_read_b128 v[196:199], v204 offset:53248
	ds_read_b128 v[206:209], v204 offset:54272
	ds_read_b128 v[210:213], v204 offset:55296
	ds_read_b128 v[214:217], v204 offset:56320
	global_load_lds_dwordx4 v[200:201], off
	s_add_i32 m0, s36, 0x2000
	s_add_u32 s12, s12, 0x40080
	v_lshl_add_u64 v[200:201], v[218:219], 0, s[96:97]
	s_addc_u32 s13, s13, 0
	s_add_i32 s36, s57, s42
	global_load_lds_dwordx4 v[200:201], off
	v_lshl_add_u64 v[200:201], s[12:13], 0, v[180:181]
	s_mov_b32 m0, s36
	s_nop 0
	global_load_lds_dwordx4 v[200:201], off
	v_lshl_add_u64 v[200:201], s[12:13], 0, v[170:171]
	s_add_i32 m0, s36, 0x2000
	s_nop 0
	global_load_lds_dwordx4 v[200:201], off
	v_lshl_add_u64 v[200:201], v[220:221], 0, s[96:97]
	s_mov_b32 m0, s50
	s_nop 0
	global_load_lds_dwordx4 v[200:201], off
	v_lshl_add_u64 v[200:201], v[222:223], 0, s[96:97]
	s_mov_b32 m0, s51
	s_nop 0
	global_load_lds_dwordx4 v[200:201], off
	s_waitcnt vmcnt(8)
	s_waitcnt lgkmcnt(0)
	s_barrier
	s_waitcnt lgkmcnt(0)
	v_mfma_f32_16x16x32_bf16 v[62:65], v[66:69], v[162:165], v[62:65]
	v_mfma_f32_16x16x32_bf16 v[58:61], v[82:85], v[162:165], v[58:61]
	v_mfma_f32_16x16x32_bf16 v[46:49], v[66:69], v[188:191], v[46:49]
	v_mfma_f32_16x16x32_bf16 v[42:45], v[82:85], v[188:191], v[42:45]
	v_mfma_f32_16x16x32_bf16 v[30:33], v[66:69], v[196:199], v[30:33]
	v_mfma_f32_16x16x32_bf16 v[26:29], v[82:85], v[196:199], v[26:29]
	v_mfma_f32_16x16x32_bf16 v[14:17], v[66:69], v[210:213], v[14:17]
	v_mfma_f32_16x16x32_bf16 v[10:13], v[82:85], v[210:213], v[10:13]
	v_mfma_f32_16x16x32_bf16 v[62:65], v[70:73], v[166:169], v[62:65]
	v_mfma_f32_16x16x32_bf16 v[58:61], v[94:97], v[166:169], v[58:61]
	v_mfma_f32_16x16x32_bf16 v[46:49], v[70:73], v[192:195], v[46:49]
	v_mfma_f32_16x16x32_bf16 v[42:45], v[94:97], v[192:195], v[42:45]
	v_mfma_f32_16x16x32_bf16 v[30:33], v[70:73], v[206:209], v[30:33]
	v_mfma_f32_16x16x32_bf16 v[26:29], v[94:97], v[206:209], v[26:29]
	v_mfma_f32_16x16x32_bf16 v[14:17], v[70:73], v[214:217], v[14:17]
	v_mfma_f32_16x16x32_bf16 v[10:13], v[94:97], v[214:217], v[10:13]
	v_mfma_f32_16x16x32_bf16 v[54:57], v[106:109], v[162:165], v[54:57]
	v_mfma_f32_16x16x32_bf16 v[50:53], v[130:133], v[162:165], v[50:53]
	v_mfma_f32_16x16x32_bf16 v[38:41], v[106:109], v[188:191], v[38:41]
	v_mfma_f32_16x16x32_bf16 v[34:37], v[130:133], v[188:191], v[34:37]
	v_mfma_f32_16x16x32_bf16 v[22:25], v[106:109], v[196:199], v[22:25]
	v_mfma_f32_16x16x32_bf16 v[18:21], v[130:133], v[196:199], v[18:21]
	v_mfma_f32_16x16x32_bf16 v[6:9], v[106:109], v[210:213], v[6:9]
	v_mfma_f32_16x16x32_bf16 v[2:5], v[130:133], v[210:213], v[2:5]
	v_mfma_f32_16x16x32_bf16 v[54:57], v[118:121], v[166:169], v[54:57]
	v_mfma_f32_16x16x32_bf16 v[50:53], v[134:137], v[166:169], v[50:53]
	v_mfma_f32_16x16x32_bf16 v[38:41], v[118:121], v[192:195], v[38:41]
	v_mfma_f32_16x16x32_bf16 v[34:37], v[134:137], v[192:195], v[34:37]
	v_mfma_f32_16x16x32_bf16 v[22:25], v[118:121], v[206:209], v[22:25]
	v_mfma_f32_16x16x32_bf16 v[18:21], v[134:137], v[206:209], v[18:21]
	v_mfma_f32_16x16x32_bf16 v[6:9], v[118:121], v[214:217], v[6:9]
	v_mfma_f32_16x16x32_bf16 v[2:5], v[134:137], v[214:217], v[2:5]
	s_barrier
	s_add_i32 s55, s55, 2
	s_add_u32 s10, s10, 0x100
	s_addc_u32 s11, s11, 0
	s_add_u32 s33, s33, 0x100
	s_addc_u32 s54, s54, 0
	s_cmp_gt_u32 s55, 13
	s_cbranch_scc0 .LBB0_633
	s_setprio 0
	s_and_b64 vcc, exec, s[20:21]
	s_cbranch_vccz .LBB0_636
	s_barrier

; template <class Epi, class Sched, bool ALIGN_EPI = false, bool SP2 = false>
; __device__ __forceinline__ void gemm_phase(PG8_LAS unsigned char* lds, const Gemm g, const Sched& S, const Epi& E) {
;     ...
;         const bool has_next = S.next(ui + 1, nxt);
;         const char* nA = has_next ? (const char*)g.A + (size_t)nxt.pm * tstep : cA; const char* nB = has_next ? (const char*)g.Bt + (size_t)nxt.pn * tstep : cB;
;         for (int t = 0; t < nt; t += 2) {
;             const bool last = (t == nt - 2);
;             const char* a1 = cA + (size_t)(t + 1) * kstep;
;             const char* a2 = last ? nA : cA + (size_t)(t + 2) * kstep; const char* b2 = last ? nB : cB + (size_t)(t + 2) * kstep;
;             const char* a3 = a2 + kstep; const char* b3 = b2 + kstep;
;             if (last && has_next) S.a_ready(nxt);
.LBB0_811:
	s_ashr_i32 s19, s18, 31
	s_lshl_b64 s[20:21], s[18:19], 19
	s_add_u32 s20, s2, s20
	s_addc_u32 s21, s30, s21
	s_and_b64 s[22:23], s[6:7], exec
	s_cselect_b32 s19, s21, s25
	s_cselect_b32 s33, s20, s24
	s_ashr_i32 s17, s16, 31
	s_lshl_b64 s[22:23], s[16:17], 19
	s_add_u32 s22, s31, s22
	s_addc_u32 s23, s34, s23
	s_and_b64 s[28:29], s[6:7], exec
	s_cselect_b32 s17, s23, s27
	s_cselect_b32 s45, s22, s26
	s_add_u32 s24, s24, 0x40080
	s_addc_u32 s25, s25, 0
	s_add_u32 s46, s26, 0x100
	s_addc_u32 s47, s27, 0
	s_mov_b32 s48, -2
	s_cmp_eq_u64 s[14:15], 0
	s_cbranch_scc0 .Lmy_prio_812
	s_setprio 1

; #define PG8_STAGE(bufoff, gbase, voff) do { _Pragma("unroll") for (int _i = 0; _i < 2; ++_i) \
;         __builtin_amdgcn_global_load_lds((const unsigned*)((const char*)(gbase) + (voff)[_i]), (PG8_LAS unsigned*)(lds + (bufoff) + ldsw + _i * 8192), 16, 0, 0); } while (0)
; #define PG8_LDA(dst, b, h) do { _Pragma("unroll") for (int m = 0; m < 4; ++m) _Pragma("unroll") for (int k = 0; k < 2; ++k) dst[m][k] = *(const PG8_LAS bf16x8*)(lds + PG8_SA(b, h) + aoff + m * 2048 + k * 1024); } while (0)
; #define PG8_MMA(ai, bj, At, Bt) do { __builtin_amdgcn_s_setprio(1); _Pragma("unroll") for (int m = 0; m < 4; ++m) _Pragma("unroll") for (int n = 0; n < 2; ++n) _Pragma("unroll") for (int k = 0; k < 2; ++k) \
;         acc[ai][bj][m][n] = __builtin_amdgcn_mfma_f32_16x16x32_bf16(Bt[n][k], At[m][k], acc[ai][bj][m][n], 0, 0, 0); __builtin_amdgcn_s_setprio(0); } while (0)
; #define PG8_WAIT_V(n) asm volatile("s_waitcnt vmcnt(" #n ")" ::: "memory")
; #define PG8_WAIT_L(n) asm volatile("s_waitcnt lgkmcnt(" #n ")" ::: "memory")
; #define PG8_BAR __builtin_amdgcn_s_barrier()
; #define PG8_SCHED __builtin_amdgcn_sched_barrier(0)
; template <class Epi, class Sched, bool ALIGN_EPI = false, bool SP2 = false>
; __device__ __forceinline__ void gemm_phase(PG8_LAS unsigned char* lds, const Gemm g, const Sched& S, const Epi& E) {
;     ...
;             PG8_WAIT_V(8); PG8_WAIT_L(0); PG8_BAR; PG8_MMA(0, 0, At, B0); PG8_MMA(0, 1, At, B1); PG8_BAR; PG8_SCHED;
;             PG8_LDA(At, 0, 1); PG8_STAGE(PG8_SB(0, 0), b2, voffB); PG8_STAGE(PG8_SB(0, 1), b2 + hstep, voffB); PG8_STAGE(PG8_SA(0, 0), a2, voffA);
;             PG8_WAIT_V(8); PG8_WAIT_L(0); PG8_BAR; PG8_MMA(1, 0, At, B0); PG8_MMA(1, 1, At, B1); PG8_BAR; PG8_SCHED;
.Levin_noz:
	s_waitcnt vmcnt(8)
	s_waitcnt lgkmcnt(0)
	s_barrier
	s_waitcnt lgkmcnt(0)
	v_mfma_f32_16x16x32_bf16 v[126:129], v[150:153], v[188:191], v[126:129]
	v_mfma_f32_16x16x32_bf16 v[122:125], v[158:161], v[188:191], v[122:125]
	v_mfma_f32_16x16x32_bf16 v[114:117], v[150:153], v[196:199], v[114:117]
	v_mfma_f32_16x16x32_bf16 v[106:109], v[158:161], v[196:199], v[106:109]
	v_mfma_f32_16x16x32_bf16 v[98:101], v[150:153], v[204:207], v[98:101]
	v_mfma_f32_16x16x32_bf16 v[90:93], v[158:161], v[204:207], v[90:93]
	v_mfma_f32_16x16x32_bf16 v[82:85], v[150:153], v[212:215], v[82:85]
	v_mfma_f32_16x16x32_bf16 v[74:77], v[158:161], v[212:215], v[74:77]
	v_mfma_f32_16x16x32_bf16 v[126:129], v[154:157], v[192:195], v[126:129]
	v_mfma_f32_16x16x32_bf16 v[122:125], v[162:165], v[192:195], v[122:125]
	v_mfma_f32_16x16x32_bf16 v[114:117], v[154:157], v[200:203], v[114:117]
	v_mfma_f32_16x16x32_bf16 v[106:109], v[162:165], v[200:203], v[106:109]
	v_mfma_f32_16x16x32_bf16 v[98:101], v[154:157], v[208:211], v[98:101]
	v_mfma_f32_16x16x32_bf16 v[90:93], v[162:165], v[208:211], v[90:93]
	v_mfma_f32_16x16x32_bf16 v[82:85], v[154:157], v[216:219], v[82:85]
	v_mfma_f32_16x16x32_bf16 v[74:77], v[162:165], v[216:219], v[74:77]
	v_mfma_f32_16x16x32_bf16 v[118:121], v[166:169], v[188:191], v[118:121]
	v_mfma_f32_16x16x32_bf16 v[110:113], v[180:183], v[188:191], v[110:113]
	v_mfma_f32_16x16x32_bf16 v[102:105], v[166:169], v[196:199], v[102:105]
	v_mfma_f32_16x16x32_bf16 v[94:97], v[180:183], v[196:199], v[94:97]
	v_mfma_f32_16x16x32_bf16 v[86:89], v[166:169], v[204:207], v[86:89]
	v_mfma_f32_16x16x32_bf16 v[78:81], v[180:183], v[204:207], v[78:81]
	v_mfma_f32_16x16x32_bf16 v[70:73], v[166:169], v[212:215], v[70:73]
	v_mfma_f32_16x16x32_bf16 v[66:69], v[180:183], v[212:215], v[66:69]
	v_mfma_f32_16x16x32_bf16 v[118:121], v[170:173], v[192:195], v[118:121]
	v_mfma_f32_16x16x32_bf16 v[110:113], v[184:187], v[192:195], v[110:113]
	v_mfma_f32_16x16x32_bf16 v[102:105], v[170:173], v[200:203], v[102:105]
	v_mfma_f32_16x16x32_bf16 v[94:97], v[184:187], v[200:203], v[94:97]
	v_mfma_f32_16x16x32_bf16 v[86:89], v[170:173], v[208:211], v[86:89]
	v_mfma_f32_16x16x32_bf16 v[78:81], v[184:187], v[208:211], v[78:81]
	v_mfma_f32_16x16x32_bf16 v[70:73], v[170:173], v[216:219], v[70:73]
	v_mfma_f32_16x16x32_bf16 v[66:69], v[184:187], v[216:219], v[66:69]
	s_barrier
	s_add_i32 s49, s49, s35
	v_lshl_add_u64 v[146:147], s[26:27], 0, v[134:135]
	s_mov_b32 m0, s49
	ds_read_b128 v[188:191], v149 offset:16384
	ds_read_b128 v[192:195], v149 offset:17408
	ds_read_b128 v[196:199], v149 offset:18432
	ds_read_b128 v[200:203], v149 offset:19456
	ds_read_b128 v[204:207], v149 offset:20480
	ds_read_b128 v[208:211], v149 offset:21504
	ds_read_b128 v[212:215], v149 offset:22528
	ds_read_b128 v[216:219], v149 offset:23552
	global_load_lds_dwordx4 v[146:147], off
	s_add_i32 m0, s49, 0x2000
	s_add_u32 s50, s26, 0x40000
	v_lshl_add_u64 v[220:221], s[26:27], 0, v[130:131]
	s_addc_u32 s51, s27, 0
	s_add_i32 s49, s52, s35
	global_load_lds_dwordx4 v[220:221], off
	v_lshl_add_u64 v[222:223], s[50:51], 0, v[134:135]
	s_mov_b32 m0, s49
	v_lshl_add_u64 v[228:229], s[28:29], 0, v[132:133]
	global_load_lds_dwordx4 v[222:223], off
	v_lshl_add_u64 v[222:223], s[50:51], 0, v[130:131]
	s_add_i32 m0, s49, 0x2000
	s_nop 0
	global_load_lds_dwordx4 v[222:223], off
	v_lshl_add_u64 v[222:223], s[28:29], 0, v[136:137]
	s_mov_b32 m0, s36
	s_nop 0
	global_load_lds_dwordx4 v[222:223], off
	s_mov_b32 m0, s37
	s_nop 0
	global_load_lds_dwordx4 v[228:229], off
	s_waitcnt vmcnt(8)
	s_waitcnt lgkmcnt(0)
	s_barrier
	s_waitcnt lgkmcnt(0)
	v_mfma_f32_16x16x32_bf16 v[62:65], v[150:153], v[188:191], v[62:65]
	v_mfma_f32_16x16x32_bf16 v[58:61], v[158:161], v[188:191], v[58:61]
	v_mfma_f32_16x16x32_bf16 v[50:53], v[150:153], v[196:199], v[50:53]
	v_mfma_f32_16x16x32_bf16 v[42:45], v[158:161], v[196:199], v[42:45]
	v_mfma_f32_16x16x32_bf16 v[34:37], v[150:153], v[204:207], v[34:37]
	v_mfma_f32_16x16x32_bf16 v[26:29], v[158:161], v[204:207], v[26:29]
	v_mfma_f32_16x16x32_bf16 v[18:21], v[150:153], v[212:215], v[18:21]
	v_mfma_f32_16x16x32_bf16 v[10:13], v[158:161], v[212:215], v[10:13]
	v_mfma_f32_16x16x32_bf16 v[62:65], v[154:157], v[192:195], v[62:65]
	v_mfma_f32_16x16x32_bf16 v[58:61], v[162:165], v[192:195], v[58:61]
	v_mfma_f32_16x16x32_bf16 v[50:53], v[154:157], v[200:203], v[50:53]
	v_mfma_f32_16x16x32_bf16 v[42:45], v[162:165], v[200:203], v[42:45]
	v_mfma_f32_16x16x32_bf16 v[34:37], v[154:157], v[208:211], v[34:37]
	v_mfma_f32_16x16x32_bf16 v[26:29], v[162:165], v[208:211], v[26:29]
	v_mfma_f32_16x16x32_bf16 v[18:21], v[154:157], v[216:219], v[18:21]
	v_mfma_f32_16x16x32_bf16 v[10:13], v[162:165], v[216:219], v[10:13]
	v_mfma_f32_16x16x32_bf16 v[54:57], v[166:169], v[188:191], v[54:57]
	v_mfma_f32_16x16x32_bf16 v[46:49], v[180:183], v[188:191], v[46:49]
	v_mfma_f32_16x16x32_bf16 v[38:41], v[166:169], v[196:199], v[38:41]
	v_mfma_f32_16x16x32_bf16 v[30:33], v[180:183], v[196:199], v[30:33]
	v_mfma_f32_16x16x32_bf16 v[22:25], v[166:169], v[204:207], v[22:25]
	v_mfma_f32_16x16x32_bf16 v[14:17], v[180:183], v[204:207], v[14:17]
	v_mfma_f32_16x16x32_bf16 v[6:9], v[166:169], v[212:215], v[6:9]
	v_mfma_f32_16x16x32_bf16 v[2:5], v[180:183], v[212:215], v[2:5]
	v_mfma_f32_16x16x32_bf16 v[54:57], v[170:173], v[192:195], v[54:57]
	v_mfma_f32_16x16x32_bf16 v[46:49], v[184:187], v[192:195], v[46:49]
	v_mfma_f32_16x16x32_bf16 v[38:41], v[170:173], v[200:203], v[38:41]
	v_mfma_f32_16x16x32_bf16 v[30:33], v[184:187], v[200:203], v[30:33]
	v_mfma_f32_16x16x32_bf16 v[22:25], v[170:173], v[208:211], v[22:25]
	v_mfma_f32_16x16x32_bf16 v[14:17], v[184:187], v[208:211], v[14:17]
	v_mfma_f32_16x16x32_bf16 v[6:9], v[170:173], v[216:219], v[6:9]
	v_mfma_f32_16x16x32_bf16 v[2:5], v[184:187], v[216:219], v[2:5]
	s_barrier
; #define PG8_STAGE(bufoff, gbase, voff) do { _Pragma("unroll") for (int _i = 0; _i < 2; ++_i) \
;         __builtin_amdgcn_global_load_lds((const unsigned*)((const char*)(gbase) + (voff)[_i]), (PG8_LAS unsigned*)(lds + (bufoff) + ldsw + _i * 8192), 16, 0, 0); } while (0)
; #define PG8_LDA(dst, b, h) do { _Pragma("unroll") for (int m = 0; m < 4; ++m) _Pragma("unroll") for (int k = 0; k < 2; ++k) dst[m][k] = *(const PG8_LAS bf16x8*)(lds + PG8_SA(b, h) + aoff + m * 2048 + k * 1024); } while (0)
; #define PG8_LDB(dst, b, h) do { _Pragma("unroll") for (int n = 0; n < 2; ++n) _Pragma("unroll") for (int k = 0; k < 2; ++k) dst[n][k] = *(const PG8_LAS bf16x8*)(lds + PG8_SB(b, h) + boff + n * 2048 + k * 1024); } while (0)
; #define PG8_MMA(ai, bj, At, Bt) do { __builtin_amdgcn_s_setprio(1); _Pragma("unroll") for (int m = 0; m < 4; ++m) _Pragma("unroll") for (int n = 0; n < 2; ++n) _Pragma("unroll") for (int k = 0; k < 2; ++k) \
;         acc[ai][bj][m][n] = __builtin_amdgcn_mfma_f32_16x16x32_bf16(Bt[n][k], At[m][k], acc[ai][bj][m][n], 0, 0, 0); __builtin_amdgcn_s_setprio(0); } while (0)
; #define PG8_WAIT_V(n) asm volatile("s_waitcnt vmcnt(" #n ")" ::: "memory")
; #define PG8_WAIT_L(n) asm volatile("s_waitcnt lgkmcnt(" #n ")" ::: "memory")
; #define PG8_BAR __builtin_amdgcn_s_barrier()
; #define PG8_SCHED __builtin_amdgcn_sched_barrier(0)
; template <class Epi, class Sched, bool ALIGN_EPI = false, bool SP2 = false>
; __device__ __forceinline__ void gemm_phase(PG8_LAS unsigned char* lds, const Gemm g, const Sched& S, const Epi& E) {
;     ...
;             PG8_LDB(B0, 1, 0); PG8_LDB(B1, 1, 1); PG8_SCHED; PG8_LDA(At, 1, 0); PG8_STAGE(PG8_SA(0, 1), a2 + hstep, voffA);
;             PG8_WAIT_V(8); PG8_WAIT_L(0); PG8_BAR; PG8_MMA(0, 0, At, B0); PG8_MMA(0, 1, At, B1); PG8_BAR; PG8_SCHED;
	s_add_i32 s49, 0, 0x18000
	v_add_u32_e32 v142, s49, v145
	s_add_i32 s50, 0, 0x1c000
	ds_read_b128 v[150:153], v142
	ds_read_b128 v[154:157], v142 offset:1024
	ds_read_b128 v[158:161], v142 offset:2048
	ds_read_b128 v[162:165], v142 offset:3072
	v_add_u32_e32 v142, s50, v145
	ds_read_b128 v[166:169], v142
	ds_read_b128 v[170:173], v142 offset:1024
	ds_read_b128 v[180:183], v142 offset:2048
	ds_read_b128 v[184:187], v142 offset:3072
	s_add_u32 s28, s28, 0x40000
	s_addc_u32 s29, s29, 0
	s_mov_b32 m0, s38
	v_lshl_add_u64 v[230:231], s[28:29], 0, v[136:137]
	ds_read_b128 v[188:191], v149 offset:32768
	ds_read_b128 v[192:195], v149 offset:33792
	ds_read_b128 v[196:199], v149 offset:34816
	ds_read_b128 v[200:203], v149 offset:35840
	ds_read_b128 v[204:207], v149 offset:36864
	ds_read_b128 v[208:211], v149 offset:37888
	ds_read_b128 v[212:215], v149 offset:38912
	ds_read_b128 v[216:219], v149 offset:39936
	global_load_lds_dwordx4 v[230:231], off
	v_lshl_add_u64 v[230:231], s[28:29], 0, v[132:133]
	s_mov_b32 m0, s39
	s_nop 0
	global_load_lds_dwordx4 v[230:231], off
	s_waitcnt vmcnt(8)
	s_waitcnt lgkmcnt(0)
	s_barrier
	s_waitcnt lgkmcnt(0)
	v_mfma_f32_16x16x32_bf16 v[126:129], v[150:153], v[188:191], v[126:129]
	v_mfma_f32_16x16x32_bf16 v[122:125], v[158:161], v[188:191], v[122:125]
	v_mfma_f32_16x16x32_bf16 v[114:117], v[150:153], v[196:199], v[114:117]
	v_mfma_f32_16x16x32_bf16 v[106:109], v[158:161], v[196:199], v[106:109]
	v_mfma_f32_16x16x32_bf16 v[98:101], v[150:153], v[204:207], v[98:101]
	v_mfma_f32_16x16x32_bf16 v[90:93], v[158:161], v[204:207], v[90:93]
	v_mfma_f32_16x16x32_bf16 v[82:85], v[150:153], v[212:215], v[82:85]
	v_mfma_f32_16x16x32_bf16 v[74:77], v[158:161], v[212:215], v[74:77]
	v_mfma_f32_16x16x32_bf16 v[126:129], v[154:157], v[192:195], v[126:129]
	v_mfma_f32_16x16x32_bf16 v[122:125], v[162:165], v[192:195], v[122:125]
	v_mfma_f32_16x16x32_bf16 v[114:117], v[154:157], v[200:203], v[114:117]
	v_mfma_f32_16x16x32_bf16 v[106:109], v[162:165], v[200:203], v[106:109]
	v_mfma_f32_16x16x32_bf16 v[98:101], v[154:157], v[208:211], v[98:101]
	v_mfma_f32_16x16x32_bf16 v[90:93], v[162:165], v[208:211], v[90:93]
	v_mfma_f32_16x16x32_bf16 v[82:85], v[154:157], v[216:219], v[82:85]
	v_mfma_f32_16x16x32_bf16 v[74:77], v[162:165], v[216:219], v[74:77]
	v_mfma_f32_16x16x32_bf16 v[118:121], v[166:169], v[188:191], v[118:121]
	v_mfma_f32_16x16x32_bf16 v[110:113], v[180:183], v[188:191], v[110:113]
	v_mfma_f32_16x16x32_bf16 v[102:105], v[166:169], v[196:199], v[102:105]
	v_mfma_f32_16x16x32_bf16 v[94:97], v[180:183], v[196:199], v[94:97]
	v_mfma_f32_16x16x32_bf16 v[86:89], v[166:169], v[204:207], v[86:89]
	v_mfma_f32_16x16x32_bf16 v[78:81], v[180:183], v[204:207], v[78:81]
	v_mfma_f32_16x16x32_bf16 v[70:73], v[166:169], v[212:215], v[70:73]
	v_mfma_f32_16x16x32_bf16 v[66:69], v[180:183], v[212:215], v[66:69]
	v_mfma_f32_16x16x32_bf16 v[118:121], v[170:173], v[192:195], v[118:121]
	v_mfma_f32_16x16x32_bf16 v[110:113], v[184:187], v[192:195], v[110:113]
	v_mfma_f32_16x16x32_bf16 v[102:105], v[170:173], v[200:203], v[102:105]
	v_mfma_f32_16x16x32_bf16 v[94:97], v[184:187], v[200:203], v[94:97]
	v_mfma_f32_16x16x32_bf16 v[86:89], v[170:173], v[208:211], v[86:89]
	v_mfma_f32_16x16x32_bf16 v[78:81], v[184:187], v[208:211], v[78:81]
	v_mfma_f32_16x16x32_bf16 v[70:73], v[170:173], v[216:219], v[70:73]
	v_mfma_f32_16x16x32_bf16 v[66:69], v[184:187], v[216:219], v[66:69]
	s_barrier
; #define PG8_STAGE(bufoff, gbase, voff) do { _Pragma("unroll") for (int _i = 0; _i < 2; ++_i) \
;         __builtin_amdgcn_global_load_lds((const unsigned*)((const char*)(gbase) + (voff)[_i]), (PG8_LAS unsigned*)(lds + (bufoff) + ldsw + _i * 8192), 16, 0, 0); } while (0)
; #define PG8_LDA(dst, b, h) do { _Pragma("unroll") for (int m = 0; m < 4; ++m) _Pragma("unroll") for (int k = 0; k < 2; ++k) dst[m][k] = *(const PG8_LAS bf16x8*)(lds + PG8_SA(b, h) + aoff + m * 2048 + k * 1024); } while (0)
; #define PG8_MMA(ai, bj, At, Bt) do { __builtin_amdgcn_s_setprio(1); _Pragma("unroll") for (int m = 0; m < 4; ++m) _Pragma("unroll") for (int n = 0; n < 2; ++n) _Pragma("unroll") for (int k = 0; k < 2; ++k) \
;         acc[ai][bj][m][n] = __builtin_amdgcn_mfma_f32_16x16x32_bf16(Bt[n][k], At[m][k], acc[ai][bj][m][n], 0, 0, 0); __builtin_amdgcn_s_setprio(0); } while (0)
; #define PG8_WAIT_V(n) asm volatile("s_waitcnt vmcnt(" #n ")" ::: "memory")
; #define PG8_WAIT_L(n) asm volatile("s_waitcnt lgkmcnt(" #n ")" ::: "memory")
; #define PG8_BAR __builtin_amdgcn_s_barrier()
; #define PG8_SCHED __builtin_amdgcn_sched_barrier(0)
; template <class Epi, class Sched, bool ALIGN_EPI = false, bool SP2 = false>
; __device__ __forceinline__ void gemm_phase(PG8_LAS unsigned char* lds, const Gemm g, const Sched& S, const Epi& E) {
;     ...
;             PG8_LDA(At, 1, 1); PG8_STAGE(PG8_SB(1, 0), b3, voffB); PG8_STAGE(PG8_SB(1, 1), b3 + hstep, voffB); PG8_STAGE(PG8_SA(1, 0), a3, voffA);
;             PG8_WAIT_V(8); PG8_WAIT_L(0); PG8_BAR; PG8_MMA(1, 0, At, B0); PG8_MMA(1, 1, At, B1); PG8_BAR; PG8_SCHED;
;     ...
;         if constexpr (ALIGN_EPI) { if (wr == 0) PG8_BAR; }
	s_add_i32 s28, s49, s35
	v_lshl_add_u64 v[146:147], v[146:147], 0, s[96:97]
	s_mov_b32 m0, s28
	ds_read_b128 v[188:191], v149 offset:49152
	ds_read_b128 v[192:195], v149 offset:50176
	ds_read_b128 v[196:199], v149 offset:51200
	ds_read_b128 v[200:203], v149 offset:52224
	ds_read_b128 v[204:207], v149 offset:53248
	ds_read_b128 v[208:211], v149 offset:54272
	ds_read_b128 v[212:215], v149 offset:55296
	ds_read_b128 v[216:219], v149 offset:56320
	global_load_lds_dwordx4 v[146:147], off
	s_add_i32 m0, s28, 0x2000
	s_add_u32 s26, s26, 0x40080
	v_lshl_add_u64 v[146:147], v[220:221], 0, s[96:97]
	s_addc_u32 s27, s27, 0
	s_add_i32 s28, s50, s35
	global_load_lds_dwordx4 v[146:147], off
	v_lshl_add_u64 v[146:147], s[26:27], 0, v[134:135]
	s_mov_b32 m0, s28
	s_nop 0
	global_load_lds_dwordx4 v[146:147], off
	v_lshl_add_u64 v[146:147], s[26:27], 0, v[130:131]
	s_add_i32 m0, s28, 0x2000
	s_nop 0
	global_load_lds_dwordx4 v[146:147], off
	v_lshl_add_u64 v[146:147], v[222:223], 0, s[96:97]
	s_mov_b32 m0, s42
	s_nop 0
	global_load_lds_dwordx4 v[146:147], off
	v_lshl_add_u64 v[146:147], v[228:229], 0, s[96:97]
	s_mov_b32 m0, s43
	s_nop 0
	global_load_lds_dwordx4 v[146:147], off
	s_waitcnt vmcnt(8)
	s_waitcnt lgkmcnt(0)
	s_barrier
	s_waitcnt lgkmcnt(0)
	v_mfma_f32_16x16x32_bf16 v[62:65], v[150:153], v[188:191], v[62:65]
	v_mfma_f32_16x16x32_bf16 v[58:61], v[158:161], v[188:191], v[58:61]
	v_mfma_f32_16x16x32_bf16 v[50:53], v[150:153], v[196:199], v[50:53]
	v_mfma_f32_16x16x32_bf16 v[42:45], v[158:161], v[196:199], v[42:45]
	v_mfma_f32_16x16x32_bf16 v[34:37], v[150:153], v[204:207], v[34:37]
	v_mfma_f32_16x16x32_bf16 v[26:29], v[158:161], v[204:207], v[26:29]
	v_mfma_f32_16x16x32_bf16 v[18:21], v[150:153], v[212:215], v[18:21]
	v_mfma_f32_16x16x32_bf16 v[10:13], v[158:161], v[212:215], v[10:13]
	v_mfma_f32_16x16x32_bf16 v[62:65], v[154:157], v[192:195], v[62:65]
	v_mfma_f32_16x16x32_bf16 v[58:61], v[162:165], v[192:195], v[58:61]
	v_mfma_f32_16x16x32_bf16 v[50:53], v[154:157], v[200:203], v[50:53]
	v_mfma_f32_16x16x32_bf16 v[42:45], v[162:165], v[200:203], v[42:45]
	v_mfma_f32_16x16x32_bf16 v[34:37], v[154:157], v[208:211], v[34:37]
	v_mfma_f32_16x16x32_bf16 v[26:29], v[162:165], v[208:211], v[26:29]
	v_mfma_f32_16x16x32_bf16 v[18:21], v[154:157], v[216:219], v[18:21]
	v_mfma_f32_16x16x32_bf16 v[10:13], v[162:165], v[216:219], v[10:13]
	v_mfma_f32_16x16x32_bf16 v[54:57], v[166:169], v[188:191], v[54:57]
	v_mfma_f32_16x16x32_bf16 v[46:49], v[180:183], v[188:191], v[46:49]
	v_mfma_f32_16x16x32_bf16 v[38:41], v[166:169], v[196:199], v[38:41]
	v_mfma_f32_16x16x32_bf16 v[30:33], v[180:183], v[196:199], v[30:33]
	v_mfma_f32_16x16x32_bf16 v[22:25], v[166:169], v[204:207], v[22:25]
	v_mfma_f32_16x16x32_bf16 v[14:17], v[180:183], v[204:207], v[14:17]
	v_mfma_f32_16x16x32_bf16 v[6:9], v[166:169], v[212:215], v[6:9]
	v_mfma_f32_16x16x32_bf16 v[2:5], v[180:183], v[212:215], v[2:5]
	v_mfma_f32_16x16x32_bf16 v[54:57], v[170:173], v[192:195], v[54:57]
	v_mfma_f32_16x16x32_bf16 v[46:49], v[184:187], v[192:195], v[46:49]
	v_mfma_f32_16x16x32_bf16 v[38:41], v[170:173], v[200:203], v[38:41]
	v_mfma_f32_16x16x32_bf16 v[30:33], v[184:187], v[200:203], v[30:33]
	v_mfma_f32_16x16x32_bf16 v[22:25], v[170:173], v[208:211], v[22:25]
	v_mfma_f32_16x16x32_bf16 v[14:17], v[184:187], v[208:211], v[14:17]
	v_mfma_f32_16x16x32_bf16 v[6:9], v[170:173], v[216:219], v[6:9]
	v_mfma_f32_16x16x32_bf16 v[2:5], v[184:187], v[216:219], v[2:5]
	s_barrier
	s_add_i32 s48, s48, 2
	s_add_u32 s24, s24, 0x100
	s_addc_u32 s25, s25, 0
	s_add_u32 s46, s46, 0x100
	s_addc_u32 s47, s47, 0
	s_cmp_gt_u32 s48, 13
	s_cbranch_scc0 .LBB0_812
	s_setprio 0
	s_and_b64 vcc, exec, s[14:15]
	s_cbranch_vccz .LBB0_815
	s_barrier

; template <class Epi, class Sched, bool ALIGN_EPI = false, bool SP2 = false>
; __device__ __forceinline__ void gemm_phase(PG8_LAS unsigned char* lds, const Gemm g, const Sched& S, const Epi& E) {
;     ...
;         const bool has_next = S.next(ui + 1, nxt);
;         const char* nA = has_next ? (const char*)g.A + (size_t)nxt.pm * tstep : cA; const char* nB = has_next ? (const char*)g.Bt + (size_t)nxt.pn * tstep : cB;
;         for (int t = 0; t < nt; t += 2) {
;             const bool last = (t == nt - 2);
;             const char* a1 = cA + (size_t)(t + 1) * kstep;
;             const char* a2 = last ? nA : cA + (size_t)(t + 2) * kstep; const char* b2 = last ? nB : cB + (size_t)(t + 2) * kstep;
;             const char* a3 = a2 + kstep; const char* b3 = b2 + kstep;
;             if (last && has_next) S.a_ready(nxt);
.LBB0_1074:
	s_ashr_i32 s29, s28, 31
	s_lshl_b64 s[30:31], s[28:29], 19
	s_add_u32 s30, s2, s30
	s_addc_u32 s31, s39, s31
	s_and_b64 s[34:35], s[6:7], exec
	s_cselect_b32 s5, s31, s9
	s_cselect_b32 s25, s30, s8
	s_ashr_i32 s27, s26, 31
	s_lshl_b64 s[34:35], s[26:27], 19
	s_add_u32 s34, s40, s34
	s_addc_u32 s35, s41, s35
	s_and_b64 s[36:37], s[6:7], exec
	s_cselect_b32 s27, s35, s11
	s_cselect_b32 s29, s34, s10
	s_add_u32 s8, s8, 0x40080
	s_addc_u32 s9, s9, 0
	s_add_u32 s33, s10, 0x100
	s_addc_u32 s54, s11, 0
	s_mov_b32 s55, -2
	s_waitcnt lgkmcnt(0)
	s_cmp_eq_u64 s[20:21], 0
	s_cbranch_scc0 .Lmy_prio_1075
	s_setprio 1

; #define PG8_STAGE(bufoff, gbase, voff) do { _Pragma("unroll") for (int _i = 0; _i < 2; ++_i) \
;         __builtin_amdgcn_global_load_lds((const unsigned*)((const char*)(gbase) + (voff)[_i]), (PG8_LAS unsigned*)(lds + (bufoff) + ldsw + _i * 8192), 16, 0, 0); } while (0)
; #define PG8_LDA(dst, b, h) do { _Pragma("unroll") for (int m = 0; m < 4; ++m) _Pragma("unroll") for (int k = 0; k < 2; ++k) dst[m][k] = *(const PG8_LAS bf16x8*)(lds + PG8_SA(b, h) + aoff + m * 2048 + k * 1024); } while (0)
; #define PG8_MMA(ai, bj, At, Bt) do { __builtin_amdgcn_s_setprio(1); _Pragma("unroll") for (int m = 0; m < 4; ++m) _Pragma("unroll") for (int n = 0; n < 2; ++n) _Pragma("unroll") for (int k = 0; k < 2; ++k) \
;         acc[ai][bj][m][n] = __builtin_amdgcn_mfma_f32_16x16x32_bf16(Bt[n][k], At[m][k], acc[ai][bj][m][n], 0, 0, 0); __builtin_amdgcn_s_setprio(0); } while (0)
; #define PG8_WAIT_V(n) asm volatile("s_waitcnt vmcnt(" #n ")" ::: "memory")
; #define PG8_WAIT_L(n) asm volatile("s_waitcnt lgkmcnt(" #n ")" ::: "memory")
; #define PG8_BAR __builtin_amdgcn_s_barrier()
; #define PG8_SCHED __builtin_amdgcn_sched_barrier(0)
; template <class Epi, class Sched, bool ALIGN_EPI = false, bool SP2 = false>
; __device__ __forceinline__ void gemm_phase(PG8_LAS unsigned char* lds, const Gemm g, const Sched& S, const Epi& E) {
;     ...
;             PG8_WAIT_V(8); PG8_WAIT_L(0); PG8_BAR; PG8_MMA(0, 0, At, B0); PG8_MMA(0, 1, At, B1); PG8_BAR; PG8_SCHED;
;             PG8_LDA(At, 0, 1); PG8_STAGE(PG8_SB(0, 0), b2, voffB); PG8_STAGE(PG8_SB(0, 1), b2 + hstep, voffB); PG8_STAGE(PG8_SA(0, 0), a2, voffA);
;             PG8_WAIT_V(8); PG8_WAIT_L(0); PG8_BAR; PG8_MMA(1, 0, At, B0); PG8_MMA(1, 1, At, B1); PG8_BAR; PG8_SCHED;
.Levout_noz:
	s_waitcnt vmcnt(8)
	s_waitcnt lgkmcnt(0)
	s_barrier
	s_waitcnt lgkmcnt(0)
	v_mfma_f32_16x16x32_bf16 v[158:161], v[66:69], v[162:165], v[158:161]
	v_mfma_f32_16x16x32_bf16 v[154:157], v[82:85], v[162:165], v[154:157]
	v_mfma_f32_16x16x32_bf16 v[142:145], v[66:69], v[188:191], v[142:145]
	v_mfma_f32_16x16x32_bf16 v[138:141], v[82:85], v[188:191], v[138:141]
	v_mfma_f32_16x16x32_bf16 v[114:117], v[66:69], v[196:199], v[114:117]
	v_mfma_f32_16x16x32_bf16 v[110:113], v[82:85], v[196:199], v[110:113]
	v_mfma_f32_16x16x32_bf16 v[90:93], v[66:69], v[210:213], v[90:93]
	v_mfma_f32_16x16x32_bf16 v[86:89], v[82:85], v[210:213], v[86:89]
	v_mfma_f32_16x16x32_bf16 v[158:161], v[70:73], v[166:169], v[158:161]
	v_mfma_f32_16x16x32_bf16 v[154:157], v[94:97], v[166:169], v[154:157]
	v_mfma_f32_16x16x32_bf16 v[142:145], v[70:73], v[192:195], v[142:145]
	v_mfma_f32_16x16x32_bf16 v[138:141], v[94:97], v[192:195], v[138:141]
	v_mfma_f32_16x16x32_bf16 v[114:117], v[70:73], v[206:209], v[114:117]
	v_mfma_f32_16x16x32_bf16 v[110:113], v[94:97], v[206:209], v[110:113]
	v_mfma_f32_16x16x32_bf16 v[90:93], v[70:73], v[214:217], v[90:93]
	v_mfma_f32_16x16x32_bf16 v[86:89], v[94:97], v[214:217], v[86:89]
	v_mfma_f32_16x16x32_bf16 v[150:153], v[106:109], v[162:165], v[150:153]
	v_mfma_f32_16x16x32_bf16 v[146:149], v[130:133], v[162:165], v[146:149]
	v_mfma_f32_16x16x32_bf16 v[126:129], v[106:109], v[188:191], v[126:129]
	v_mfma_f32_16x16x32_bf16 v[122:125], v[130:133], v[188:191], v[122:125]
	v_mfma_f32_16x16x32_bf16 v[102:105], v[106:109], v[196:199], v[102:105]
	v_mfma_f32_16x16x32_bf16 v[98:101], v[130:133], v[196:199], v[98:101]
	v_mfma_f32_16x16x32_bf16 v[78:81], v[106:109], v[210:213], v[78:81]
	v_mfma_f32_16x16x32_bf16 v[74:77], v[130:133], v[210:213], v[74:77]
	v_mfma_f32_16x16x32_bf16 v[150:153], v[118:121], v[166:169], v[150:153]
	v_mfma_f32_16x16x32_bf16 v[146:149], v[134:137], v[166:169], v[146:149]
	v_mfma_f32_16x16x32_bf16 v[126:129], v[118:121], v[192:195], v[126:129]
	v_mfma_f32_16x16x32_bf16 v[122:125], v[134:137], v[192:195], v[122:125]
	v_mfma_f32_16x16x32_bf16 v[102:105], v[118:121], v[206:209], v[102:105]
	v_mfma_f32_16x16x32_bf16 v[98:101], v[134:137], v[206:209], v[98:101]
	v_mfma_f32_16x16x32_bf16 v[78:81], v[118:121], v[214:217], v[78:81]
	v_mfma_f32_16x16x32_bf16 v[74:77], v[134:137], v[214:217], v[74:77]
	s_barrier
	s_add_i32 s56, s56, s42
	v_lshl_add_u64 v[200:201], s[10:11], 0, v[180:181]
	s_mov_b32 m0, s56
	ds_read_b128 v[162:165], v204 offset:16384
	ds_read_b128 v[166:169], v204 offset:17408
	ds_read_b128 v[188:191], v204 offset:18432
	ds_read_b128 v[192:195], v204 offset:19456
	ds_read_b128 v[196:199], v204 offset:20480
	ds_read_b128 v[206:209], v204 offset:21504
	ds_read_b128 v[210:213], v204 offset:22528
	ds_read_b128 v[214:217], v204 offset:23552
	global_load_lds_dwordx4 v[200:201], off
	s_add_i32 m0, s56, 0x2000
	s_add_u32 s56, s10, 0x40000
	v_lshl_add_u64 v[218:219], s[10:11], 0, v[170:171]
	s_addc_u32 s57, s11, 0
	s_add_i32 s58, s58, s42
	global_load_lds_dwordx4 v[218:219], off
	v_lshl_add_u64 v[220:221], s[56:57], 0, v[180:181]
	s_mov_b32 m0, s58
	v_lshl_add_u64 v[222:223], s[36:37], 0, v[172:173]
	global_load_lds_dwordx4 v[220:221], off
	v_lshl_add_u64 v[220:221], s[56:57], 0, v[170:171]
	s_add_i32 m0, s58, 0x2000
	s_nop 0
	global_load_lds_dwordx4 v[220:221], off
	v_lshl_add_u64 v[220:221], s[36:37], 0, v[182:183]
	s_mov_b32 m0, s43
	s_nop 0
	global_load_lds_dwordx4 v[220:221], off
	s_mov_b32 m0, s44
	s_nop 0
	global_load_lds_dwordx4 v[222:223], off
	s_waitcnt vmcnt(8)
	s_waitcnt lgkmcnt(0)
	s_barrier
	s_waitcnt lgkmcnt(0)
	v_mfma_f32_16x16x32_bf16 v[62:65], v[66:69], v[162:165], v[62:65]
	v_mfma_f32_16x16x32_bf16 v[58:61], v[82:85], v[162:165], v[58:61]
	v_mfma_f32_16x16x32_bf16 v[46:49], v[66:69], v[188:191], v[46:49]
	v_mfma_f32_16x16x32_bf16 v[42:45], v[82:85], v[188:191], v[42:45]
	v_mfma_f32_16x16x32_bf16 v[30:33], v[66:69], v[196:199], v[30:33]
	v_mfma_f32_16x16x32_bf16 v[26:29], v[82:85], v[196:199], v[26:29]
	v_mfma_f32_16x16x32_bf16 v[14:17], v[66:69], v[210:213], v[14:17]
	v_mfma_f32_16x16x32_bf16 v[10:13], v[82:85], v[210:213], v[10:13]
	v_mfma_f32_16x16x32_bf16 v[62:65], v[70:73], v[166:169], v[62:65]
	v_mfma_f32_16x16x32_bf16 v[58:61], v[94:97], v[166:169], v[58:61]
	v_mfma_f32_16x16x32_bf16 v[46:49], v[70:73], v[192:195], v[46:49]
	v_mfma_f32_16x16x32_bf16 v[42:45], v[94:97], v[192:195], v[42:45]
	v_mfma_f32_16x16x32_bf16 v[30:33], v[70:73], v[206:209], v[30:33]
	v_mfma_f32_16x16x32_bf16 v[26:29], v[94:97], v[206:209], v[26:29]
	v_mfma_f32_16x16x32_bf16 v[14:17], v[70:73], v[214:217], v[14:17]
	v_mfma_f32_16x16x32_bf16 v[10:13], v[94:97], v[214:217], v[10:13]
	v_mfma_f32_16x16x32_bf16 v[54:57], v[106:109], v[162:165], v[54:57]
	v_mfma_f32_16x16x32_bf16 v[50:53], v[130:133], v[162:165], v[50:53]
	v_mfma_f32_16x16x32_bf16 v[38:41], v[106:109], v[188:191], v[38:41]
	v_mfma_f32_16x16x32_bf16 v[34:37], v[130:133], v[188:191], v[34:37]
	v_mfma_f32_16x16x32_bf16 v[22:25], v[106:109], v[196:199], v[22:25]
	v_mfma_f32_16x16x32_bf16 v[18:21], v[130:133], v[196:199], v[18:21]
	v_mfma_f32_16x16x32_bf16 v[6:9], v[106:109], v[210:213], v[6:9]
	v_mfma_f32_16x16x32_bf16 v[2:5], v[130:133], v[210:213], v[2:5]
	v_mfma_f32_16x16x32_bf16 v[54:57], v[118:121], v[166:169], v[54:57]
	v_mfma_f32_16x16x32_bf16 v[50:53], v[134:137], v[166:169], v[50:53]
	v_mfma_f32_16x16x32_bf16 v[38:41], v[118:121], v[192:195], v[38:41]
	v_mfma_f32_16x16x32_bf16 v[34:37], v[134:137], v[192:195], v[34:37]
	v_mfma_f32_16x16x32_bf16 v[22:25], v[118:121], v[206:209], v[22:25]
	v_mfma_f32_16x16x32_bf16 v[18:21], v[134:137], v[206:209], v[18:21]
	v_mfma_f32_16x16x32_bf16 v[6:9], v[118:121], v[214:217], v[6:9]
	v_mfma_f32_16x16x32_bf16 v[2:5], v[134:137], v[214:217], v[2:5]
	s_barrier
; #define PG8_STAGE(bufoff, gbase, voff) do { _Pragma("unroll") for (int _i = 0; _i < 2; ++_i) \
;         __builtin_amdgcn_global_load_lds((const unsigned*)((const char*)(gbase) + (voff)[_i]), (PG8_LAS unsigned*)(lds + (bufoff) + ldsw + _i * 8192), 16, 0, 0); } while (0)
; #define PG8_LDA(dst, b, h) do { _Pragma("unroll") for (int m = 0; m < 4; ++m) _Pragma("unroll") for (int k = 0; k < 2; ++k) dst[m][k] = *(const PG8_LAS bf16x8*)(lds + PG8_SA(b, h) + aoff + m * 2048 + k * 1024); } while (0)
; #define PG8_LDB(dst, b, h) do { _Pragma("unroll") for (int n = 0; n < 2; ++n) _Pragma("unroll") for (int k = 0; k < 2; ++k) dst[n][k] = *(const PG8_LAS bf16x8*)(lds + PG8_SB(b, h) + boff + n * 2048 + k * 1024); } while (0)
; #define PG8_MMA(ai, bj, At, Bt) do { __builtin_amdgcn_s_setprio(1); _Pragma("unroll") for (int m = 0; m < 4; ++m) _Pragma("unroll") for (int n = 0; n < 2; ++n) _Pragma("unroll") for (int k = 0; k < 2; ++k) \
;         acc[ai][bj][m][n] = __builtin_amdgcn_mfma_f32_16x16x32_bf16(Bt[n][k], At[m][k], acc[ai][bj][m][n], 0, 0, 0); __builtin_amdgcn_s_setprio(0); } while (0)
; #define PG8_WAIT_V(n) asm volatile("s_waitcnt vmcnt(" #n ")" ::: "memory")
; #define PG8_WAIT_L(n) asm volatile("s_waitcnt lgkmcnt(" #n ")" ::: "memory")
; #define PG8_BAR __builtin_amdgcn_s_barrier()
; #define PG8_SCHED __builtin_amdgcn_sched_barrier(0)
; template <class Epi, class Sched, bool ALIGN_EPI = false, bool SP2 = false>
; __device__ __forceinline__ void gemm_phase(PG8_LAS unsigned char* lds, const Gemm g, const Sched& S, const Epi& E) {
;     ...
;             PG8_LDB(B0, 1, 0); PG8_LDB(B1, 1, 1); PG8_SCHED; PG8_LDA(At, 1, 0); PG8_STAGE(PG8_SA(0, 1), a2 + hstep, voffA);
;             PG8_WAIT_V(8); PG8_WAIT_L(0); PG8_BAR; PG8_MMA(0, 0, At, B0); PG8_MMA(0, 1, At, B1); PG8_BAR; PG8_SCHED;
	s_add_i32 s56, 0, 0x18000
	s_add_i32 s57, 0, 0x1c000
	v_add_u32_e32 v94, s56, v203
	v_add_u32_e32 v134, s57, v203
	ds_read_b128 v[66:69], v94
	ds_read_b128 v[70:73], v94 offset:1024
	ds_read_b128 v[82:85], v94 offset:2048
	ds_read_b128 v[94:97], v94 offset:3072
	ds_read_b128 v[106:109], v134
	ds_read_b128 v[118:121], v134 offset:1024
	ds_read_b128 v[130:133], v134 offset:2048
	ds_read_b128 v[134:137], v134 offset:3072
	s_add_u32 s36, s36, 0x40000
	s_addc_u32 s37, s37, 0
	s_mov_b32 m0, s45
	v_lshl_add_u64 v[228:229], s[36:37], 0, v[182:183]
	ds_read_b128 v[162:165], v204 offset:32768
	ds_read_b128 v[166:169], v204 offset:33792
	ds_read_b128 v[188:191], v204 offset:34816
	ds_read_b128 v[192:195], v204 offset:35840
	ds_read_b128 v[196:199], v204 offset:36864
	ds_read_b128 v[206:209], v204 offset:37888
	ds_read_b128 v[210:213], v204 offset:38912
	ds_read_b128 v[214:217], v204 offset:39936
	global_load_lds_dwordx4 v[228:229], off
	v_lshl_add_u64 v[228:229], s[36:37], 0, v[172:173]
	s_mov_b32 m0, s46
	s_nop 0
	global_load_lds_dwordx4 v[228:229], off
	s_waitcnt vmcnt(8)
	s_waitcnt lgkmcnt(0)
	s_barrier
	s_waitcnt lgkmcnt(0)
	v_mfma_f32_16x16x32_bf16 v[158:161], v[66:69], v[162:165], v[158:161]
	v_mfma_f32_16x16x32_bf16 v[154:157], v[82:85], v[162:165], v[154:157]
	v_mfma_f32_16x16x32_bf16 v[142:145], v[66:69], v[188:191], v[142:145]
	v_mfma_f32_16x16x32_bf16 v[138:141], v[82:85], v[188:191], v[138:141]
	v_mfma_f32_16x16x32_bf16 v[114:117], v[66:69], v[196:199], v[114:117]
	v_mfma_f32_16x16x32_bf16 v[110:113], v[82:85], v[196:199], v[110:113]
	v_mfma_f32_16x16x32_bf16 v[90:93], v[66:69], v[210:213], v[90:93]
	v_mfma_f32_16x16x32_bf16 v[86:89], v[82:85], v[210:213], v[86:89]
	v_mfma_f32_16x16x32_bf16 v[158:161], v[70:73], v[166:169], v[158:161]
	v_mfma_f32_16x16x32_bf16 v[154:157], v[94:97], v[166:169], v[154:157]
	v_mfma_f32_16x16x32_bf16 v[142:145], v[70:73], v[192:195], v[142:145]
	v_mfma_f32_16x16x32_bf16 v[138:141], v[94:97], v[192:195], v[138:141]
	v_mfma_f32_16x16x32_bf16 v[114:117], v[70:73], v[206:209], v[114:117]
	v_mfma_f32_16x16x32_bf16 v[110:113], v[94:97], v[206:209], v[110:113]
	v_mfma_f32_16x16x32_bf16 v[90:93], v[70:73], v[214:217], v[90:93]
	v_mfma_f32_16x16x32_bf16 v[86:89], v[94:97], v[214:217], v[86:89]
	v_mfma_f32_16x16x32_bf16 v[150:153], v[106:109], v[162:165], v[150:153]
	v_mfma_f32_16x16x32_bf16 v[146:149], v[130:133], v[162:165], v[146:149]
	v_mfma_f32_16x16x32_bf16 v[126:129], v[106:109], v[188:191], v[126:129]
	v_mfma_f32_16x16x32_bf16 v[122:125], v[130:133], v[188:191], v[122:125]
	v_mfma_f32_16x16x32_bf16 v[102:105], v[106:109], v[196:199], v[102:105]
	v_mfma_f32_16x16x32_bf16 v[98:101], v[130:133], v[196:199], v[98:101]
	v_mfma_f32_16x16x32_bf16 v[78:81], v[106:109], v[210:213], v[78:81]
	v_mfma_f32_16x16x32_bf16 v[74:77], v[130:133], v[210:213], v[74:77]
	v_mfma_f32_16x16x32_bf16 v[150:153], v[118:121], v[166:169], v[150:153]
	v_mfma_f32_16x16x32_bf16 v[146:149], v[134:137], v[166:169], v[146:149]
	v_mfma_f32_16x16x32_bf16 v[126:129], v[118:121], v[192:195], v[126:129]
	v_mfma_f32_16x16x32_bf16 v[122:125], v[134:137], v[192:195], v[122:125]
	v_mfma_f32_16x16x32_bf16 v[102:105], v[118:121], v[206:209], v[102:105]
	v_mfma_f32_16x16x32_bf16 v[98:101], v[134:137], v[206:209], v[98:101]
	v_mfma_f32_16x16x32_bf16 v[78:81], v[118:121], v[214:217], v[78:81]
	v_mfma_f32_16x16x32_bf16 v[74:77], v[134:137], v[214:217], v[74:77]
	s_barrier
; #define PG8_STAGE(bufoff, gbase, voff) do { _Pragma("unroll") for (int _i = 0; _i < 2; ++_i) \
;         __builtin_amdgcn_global_load_lds((const unsigned*)((const char*)(gbase) + (voff)[_i]), (PG8_LAS unsigned*)(lds + (bufoff) + ldsw + _i * 8192), 16, 0, 0); } while (0)
; #define PG8_LDA(dst, b, h) do { _Pragma("unroll") for (int m = 0; m < 4; ++m) _Pragma("unroll") for (int k = 0; k < 2; ++k) dst[m][k] = *(const PG8_LAS bf16x8*)(lds + PG8_SA(b, h) + aoff + m * 2048 + k * 1024); } while (0)
; #define PG8_MMA(ai, bj, At, Bt) do { __builtin_amdgcn_s_setprio(1); _Pragma("unroll") for (int m = 0; m < 4; ++m) _Pragma("unroll") for (int n = 0; n < 2; ++n) _Pragma("unroll") for (int k = 0; k < 2; ++k) \
;         acc[ai][bj][m][n] = __builtin_amdgcn_mfma_f32_16x16x32_bf16(Bt[n][k], At[m][k], acc[ai][bj][m][n], 0, 0, 0); __builtin_amdgcn_s_setprio(0); } while (0)
; #define PG8_WAIT_V(n) asm volatile("s_waitcnt vmcnt(" #n ")" ::: "memory")
; #define PG8_WAIT_L(n) asm volatile("s_waitcnt lgkmcnt(" #n ")" ::: "memory")
; #define PG8_BAR __builtin_amdgcn_s_barrier()
; #define PG8_SCHED __builtin_amdgcn_sched_barrier(0)
; template <class Epi, class Sched, bool ALIGN_EPI = false, bool SP2 = false>
; __device__ __forceinline__ void gemm_phase(PG8_LAS unsigned char* lds, const Gemm g, const Sched& S, const Epi& E) {
;     ...
;             PG8_LDA(At, 1, 1); PG8_STAGE(PG8_SB(1, 0), b3, voffB); PG8_STAGE(PG8_SB(1, 1), b3 + hstep, voffB); PG8_STAGE(PG8_SA(1, 0), a3, voffA);
;             PG8_WAIT_V(8); PG8_WAIT_L(0); PG8_BAR; PG8_MMA(1, 0, At, B0); PG8_MMA(1, 1, At, B1); PG8_BAR; PG8_SCHED;
;     ...
;         if constexpr (ALIGN_EPI) { if (wr == 0) PG8_BAR; }
	s_add_i32 s36, s56, s42
	v_lshl_add_u64 v[200:201], v[200:201], 0, s[96:97]
	s_mov_b32 m0, s36
	ds_read_b128 v[162:165], v204 offset:49152
	ds_read_b128 v[166:169], v204 offset:50176
	ds_read_b128 v[188:191], v204 offset:51200
	ds_read_b128 v[192:195], v204 offset:52224
	ds_read_b128 v[196:199], v204 offset:53248
	ds_read_b128 v[206:209], v204 offset:54272
	ds_read_b128 v[210:213], v204 offset:55296
	ds_read_b128 v[214:217], v204 offset:56320
	global_load_lds_dwordx4 v[200:201], off
	s_add_i32 m0, s36, 0x2000
	s_add_u32 s10, s10, 0x40080
	v_lshl_add_u64 v[200:201], v[218:219], 0, s[96:97]
	s_addc_u32 s11, s11, 0
	s_add_i32 s36, s57, s42
	global_load_lds_dwordx4 v[200:201], off
	v_lshl_add_u64 v[200:201], s[10:11], 0, v[180:181]
	s_mov_b32 m0, s36
	s_nop 0
	global_load_lds_dwordx4 v[200:201], off
	v_lshl_add_u64 v[200:201], s[10:11], 0, v[170:171]
	s_add_i32 m0, s36, 0x2000
	s_nop 0
	global_load_lds_dwordx4 v[200:201], off
	v_lshl_add_u64 v[200:201], v[220:221], 0, s[96:97]
	s_mov_b32 m0, s50
	s_nop 0
	global_load_lds_dwordx4 v[200:201], off
	v_lshl_add_u64 v[200:201], v[222:223], 0, s[96:97]
	s_mov_b32 m0, s51
	s_nop 0
	global_load_lds_dwordx4 v[200:201], off
	s_waitcnt vmcnt(8)
	s_waitcnt lgkmcnt(0)
	s_barrier
	s_waitcnt lgkmcnt(0)
	v_mfma_f32_16x16x32_bf16 v[62:65], v[66:69], v[162:165], v[62:65]
	v_mfma_f32_16x16x32_bf16 v[58:61], v[82:85], v[162:165], v[58:61]
	v_mfma_f32_16x16x32_bf16 v[46:49], v[66:69], v[188:191], v[46:49]
	v_mfma_f32_16x16x32_bf16 v[42:45], v[82:85], v[188:191], v[42:45]
	v_mfma_f32_16x16x32_bf16 v[30:33], v[66:69], v[196:199], v[30:33]
	v_mfma_f32_16x16x32_bf16 v[26:29], v[82:85], v[196:199], v[26:29]
	v_mfma_f32_16x16x32_bf16 v[14:17], v[66:69], v[210:213], v[14:17]
	v_mfma_f32_16x16x32_bf16 v[10:13], v[82:85], v[210:213], v[10:13]
	v_mfma_f32_16x16x32_bf16 v[62:65], v[70:73], v[166:169], v[62:65]
	v_mfma_f32_16x16x32_bf16 v[58:61], v[94:97], v[166:169], v[58:61]
	v_mfma_f32_16x16x32_bf16 v[46:49], v[70:73], v[192:195], v[46:49]
	v_mfma_f32_16x16x32_bf16 v[42:45], v[94:97], v[192:195], v[42:45]
	v_mfma_f32_16x16x32_bf16 v[30:33], v[70:73], v[206:209], v[30:33]
	v_mfma_f32_16x16x32_bf16 v[26:29], v[94:97], v[206:209], v[26:29]
	v_mfma_f32_16x16x32_bf16 v[14:17], v[70:73], v[214:217], v[14:17]
	v_mfma_f32_16x16x32_bf16 v[10:13], v[94:97], v[214:217], v[10:13]
	v_mfma_f32_16x16x32_bf16 v[54:57], v[106:109], v[162:165], v[54:57]
	v_mfma_f32_16x16x32_bf16 v[50:53], v[130:133], v[162:165], v[50:53]
	v_mfma_f32_16x16x32_bf16 v[38:41], v[106:109], v[188:191], v[38:41]
	v_mfma_f32_16x16x32_bf16 v[34:37], v[130:133], v[188:191], v[34:37]
	v_mfma_f32_16x16x32_bf16 v[22:25], v[106:109], v[196:199], v[22:25]
	v_mfma_f32_16x16x32_bf16 v[18:21], v[130:133], v[196:199], v[18:21]
	v_mfma_f32_16x16x32_bf16 v[6:9], v[106:109], v[210:213], v[6:9]
	v_mfma_f32_16x16x32_bf16 v[2:5], v[130:133], v[210:213], v[2:5]
	v_mfma_f32_16x16x32_bf16 v[54:57], v[118:121], v[166:169], v[54:57]
	v_mfma_f32_16x16x32_bf16 v[50:53], v[134:137], v[166:169], v[50:53]
	v_mfma_f32_16x16x32_bf16 v[38:41], v[118:121], v[192:195], v[38:41]
	v_mfma_f32_16x16x32_bf16 v[34:37], v[134:137], v[192:195], v[34:37]
	v_mfma_f32_16x16x32_bf16 v[22:25], v[118:121], v[206:209], v[22:25]
	v_mfma_f32_16x16x32_bf16 v[18:21], v[134:137], v[206:209], v[18:21]
	v_mfma_f32_16x16x32_bf16 v[6:9], v[118:121], v[214:217], v[6:9]
	v_mfma_f32_16x16x32_bf16 v[2:5], v[134:137], v[214:217], v[2:5]
	s_barrier
	s_add_i32 s55, s55, 2
	s_add_u32 s8, s8, 0x100
	s_addc_u32 s9, s9, 0
	s_add_u32 s33, s33, 0x100
	s_addc_u32 s54, s54, 0
	s_cmp_gt_u32 s55, 13
	s_cbranch_scc0 .LBB0_1075
	s_setprio 0
	s_and_b64 vcc, exec, s[20:21]
	s_cbranch_vccz .LBB0_1078
	s_barrier

; template <class Epi, class Sched, bool ALIGN_EPI = false, bool SP2 = false>
; __device__ __forceinline__ void gemm_phase(PG8_LAS unsigned char* lds, const Gemm g, const Sched& S, const Epi& E) {
;     ...
;         const bool has_next = S.next(ui + 1, nxt);
;         const char* nA = has_next ? (const char*)g.A + (size_t)nxt.pm * tstep : cA; const char* nB = has_next ? (const char*)g.Bt + (size_t)nxt.pn * tstep : cB;
;         for (int t = 0; t < nt; t += 2) {
;             const bool last = (t == nt - 2);
;             const char* a1 = cA + (size_t)(t + 1) * kstep;
;             const char* a2 = last ? nA : cA + (size_t)(t + 2) * kstep; const char* b2 = last ? nB : cB + (size_t)(t + 2) * kstep;
;             const char* a3 = a2 + kstep; const char* b3 = b2 + kstep;
.LBB0_1246:
	s_ashr_i32 s37, s36, 31
	s_lshl_b64 s[8:9], s[36:37], 19
	s_add_u32 s38, s2, s8
	s_addc_u32 s39, s49, s9
	s_and_b64 s[8:9], s[6:7], exec
	s_cselect_b32 s37, s39, s47
	s_cselect_b32 s43, s38, s46
	s_ashr_i32 s35, s34, 31
	s_lshl_b64 s[8:9], s[34:35], 19
	s_add_u32 s40, s50, s8
	s_addc_u32 s41, s51, s9
	s_and_b64 s[8:9], s[6:7], exec
	s_cselect_b32 s35, s41, s45
	s_cselect_b32 s65, s40, s44
	s_add_u32 s8, s46, 0x40080
	s_addc_u32 s9, s47, 0
	s_add_u32 s66, s44, 0x100
	s_addc_u32 s67, s45, 0
	s_mov_b32 s68, -2
	s_cmp_eq_u64 s[24:25], 0
	s_cbranch_scc0 .Lmy_prio_1247
	s_setprio 1

; #define PG8_STAGE(bufoff, gbase, voff) do { _Pragma("unroll") for (int _i = 0; _i < 2; ++_i) \
;         __builtin_amdgcn_global_load_lds((const unsigned*)((const char*)(gbase) + (voff)[_i]), (PG8_LAS unsigned*)(lds + (bufoff) + ldsw + _i * 8192), 16, 0, 0); } while (0)
; #define PG8_LDA(dst, b, h) do { _Pragma("unroll") for (int m = 0; m < 4; ++m) _Pragma("unroll") for (int k = 0; k < 2; ++k) dst[m][k] = *(const PG8_LAS bf16x8*)(lds + PG8_SA(b, h) + aoff + m * 2048 + k * 1024); } while (0)
; #define PG8_LDB(dst, b, h) do { _Pragma("unroll") for (int n = 0; n < 2; ++n) _Pragma("unroll") for (int k = 0; k < 2; ++k) dst[n][k] = *(const PG8_LAS bf16x8*)(lds + PG8_SB(b, h) + boff + n * 2048 + k * 1024); } while (0)
; #define PG8_MMA(ai, bj, At, Bt) do { __builtin_amdgcn_s_setprio(1); _Pragma("unroll") for (int m = 0; m < 4; ++m) _Pragma("unroll") for (int n = 0; n < 2; ++n) _Pragma("unroll") for (int k = 0; k < 2; ++k) \
;         acc[ai][bj][m][n] = __builtin_amdgcn_mfma_f32_16x16x32_bf16(Bt[n][k], At[m][k], acc[ai][bj][m][n], 0, 0, 0); __builtin_amdgcn_s_setprio(0); } while (0)
; #define PG8_WAIT_V(n) asm volatile("s_waitcnt vmcnt(" #n ")" ::: "memory")
; #define PG8_WAIT_L(n) asm volatile("s_waitcnt lgkmcnt(" #n ")" ::: "memory")
; #define PG8_BAR __builtin_amdgcn_s_barrier()
; #define PG8_SCHED __builtin_amdgcn_sched_barrier(0)
; template <class Epi, class Sched, bool ALIGN_EPI = false, bool SP2 = false>
; __device__ __forceinline__ void gemm_phase(PG8_LAS unsigned char* lds, const Gemm g, const Sched& S, const Epi& E) {
;     ...
;             PG8_WAIT_V(8); PG8_WAIT_L(0); PG8_BAR; PG8_MMA(1, 0, At, B0); PG8_MMA(1, 1, At, B1); PG8_BAR; PG8_SCHED;
;             PG8_LDB(B0, 1, 0); PG8_LDB(B1, 1, 1); PG8_SCHED; PG8_LDA(At, 1, 0); PG8_STAGE(PG8_SA(0, 1), a2 + hstep, voffA);
;             PG8_WAIT_V(8); PG8_WAIT_L(0); PG8_BAR; PG8_MMA(0, 0, At, B0); PG8_MMA(0, 1, At, B1); PG8_BAR; PG8_SCHED;
.Lffin_wd:
	s_waitcnt lgkmcnt(0)
	s_barrier
	s_waitcnt lgkmcnt(0)
	v_mfma_f32_16x16x32_bf16 v[62:65], v[106:109], v[162:165], v[62:65]
	v_mfma_f32_16x16x32_bf16 v[58:61], v[114:117], v[162:165], v[58:61]
	v_mfma_f32_16x16x32_bf16 v[46:49], v[106:109], v[170:173], v[46:49]
	v_mfma_f32_16x16x32_bf16 v[42:45], v[114:117], v[170:173], v[42:45]
	v_mfma_f32_16x16x32_bf16 v[30:33], v[106:109], v[196:199], v[30:33]
	v_mfma_f32_16x16x32_bf16 v[26:29], v[114:117], v[196:199], v[26:29]
	v_mfma_f32_16x16x32_bf16 v[14:17], v[106:109], v[204:207], v[14:17]
	v_mfma_f32_16x16x32_bf16 v[10:13], v[114:117], v[204:207], v[10:13]
	v_mfma_f32_16x16x32_bf16 v[62:65], v[110:113], v[166:169], v[62:65]
	v_mfma_f32_16x16x32_bf16 v[58:61], v[118:121], v[166:169], v[58:61]
	v_mfma_f32_16x16x32_bf16 v[46:49], v[110:113], v[192:195], v[46:49]
	v_mfma_f32_16x16x32_bf16 v[42:45], v[118:121], v[192:195], v[42:45]
	v_mfma_f32_16x16x32_bf16 v[30:33], v[110:113], v[200:203], v[30:33]
	v_mfma_f32_16x16x32_bf16 v[26:29], v[118:121], v[200:203], v[26:29]
	v_mfma_f32_16x16x32_bf16 v[14:17], v[110:113], v[208:211], v[14:17]
	v_mfma_f32_16x16x32_bf16 v[10:13], v[118:121], v[208:211], v[10:13]
	v_mfma_f32_16x16x32_bf16 v[54:57], v[122:125], v[162:165], v[54:57]
	v_mfma_f32_16x16x32_bf16 v[50:53], v[130:133], v[162:165], v[50:53]
	v_mfma_f32_16x16x32_bf16 v[38:41], v[122:125], v[170:173], v[38:41]
	v_mfma_f32_16x16x32_bf16 v[34:37], v[130:133], v[170:173], v[34:37]
	v_mfma_f32_16x16x32_bf16 v[22:25], v[122:125], v[196:199], v[22:25]
	v_mfma_f32_16x16x32_bf16 v[18:21], v[130:133], v[196:199], v[18:21]
	v_mfma_f32_16x16x32_bf16 v[6:9], v[122:125], v[204:207], v[6:9]
	v_mfma_f32_16x16x32_bf16 v[2:5], v[130:133], v[204:207], v[2:5]
	v_mfma_f32_16x16x32_bf16 v[54:57], v[126:129], v[166:169], v[54:57]
	v_mfma_f32_16x16x32_bf16 v[50:53], v[134:137], v[166:169], v[50:53]
	v_mfma_f32_16x16x32_bf16 v[38:41], v[126:129], v[192:195], v[38:41]
	v_mfma_f32_16x16x32_bf16 v[34:37], v[134:137], v[192:195], v[34:37]
	v_mfma_f32_16x16x32_bf16 v[22:25], v[126:129], v[200:203], v[22:25]
	v_mfma_f32_16x16x32_bf16 v[18:21], v[134:137], v[200:203], v[18:21]
	v_mfma_f32_16x16x32_bf16 v[6:9], v[126:129], v[208:211], v[6:9]
	v_mfma_f32_16x16x32_bf16 v[2:5], v[134:137], v[208:211], v[2:5]
	s_barrier
	s_add_i32 s69, 0, 0x18000
	s_add_i32 s70, 0, 0x1c000
	v_add_u32_e32 v118, s69, v229
	v_add_u32_e32 v134, s70, v229
	ds_read_b128 v[106:109], v118
	ds_read_b128 v[110:113], v118 offset:1024
	ds_read_b128 v[114:117], v118 offset:2048
	ds_read_b128 v[118:121], v118 offset:3072
	ds_read_b128 v[122:125], v134
	ds_read_b128 v[126:129], v134 offset:1024
	ds_read_b128 v[130:133], v134 offset:2048
	ds_read_b128 v[134:137], v134 offset:3072
	s_add_u32 s46, s46, 0x40000
	s_addc_u32 s47, s47, 0
	s_mov_b32 m0, s55
	v_lshl_add_u64 v[220:221], s[46:47], 0, v[186:187]
	ds_read_b128 v[162:165], v230 offset:32768
	ds_read_b128 v[166:169], v230 offset:33792
	ds_read_b128 v[170:173], v230 offset:34816
	ds_read_b128 v[192:195], v230 offset:35840
	ds_read_b128 v[196:199], v230 offset:36864
	ds_read_b128 v[200:203], v230 offset:37888
	ds_read_b128 v[204:207], v230 offset:38912
	ds_read_b128 v[208:211], v230 offset:39936
	global_load_lds_dwordx4 v[220:221], off
	v_lshl_add_u64 v[220:221], s[46:47], 0, v[182:183]
	s_mov_b32 m0, s56
	s_nop 0
	global_load_lds_dwordx4 v[220:221], off
	s_waitcnt vmcnt(8)
	s_waitcnt lgkmcnt(0)
	s_barrier
	s_waitcnt lgkmcnt(0)
	v_mfma_f32_16x16x32_bf16 v[158:161], v[106:109], v[162:165], v[158:161]
	v_mfma_f32_16x16x32_bf16 v[154:157], v[114:117], v[162:165], v[154:157]
	v_mfma_f32_16x16x32_bf16 v[142:145], v[106:109], v[170:173], v[142:145]
	v_mfma_f32_16x16x32_bf16 v[138:141], v[114:117], v[170:173], v[138:141]
	v_mfma_f32_16x16x32_bf16 v[94:97], v[106:109], v[196:199], v[94:97]
	v_mfma_f32_16x16x32_bf16 v[90:93], v[114:117], v[196:199], v[90:93]
	v_mfma_f32_16x16x32_bf16 v[78:81], v[106:109], v[204:207], v[78:81]
	v_mfma_f32_16x16x32_bf16 v[74:77], v[114:117], v[204:207], v[74:77]
	v_mfma_f32_16x16x32_bf16 v[158:161], v[110:113], v[166:169], v[158:161]
	v_mfma_f32_16x16x32_bf16 v[154:157], v[118:121], v[166:169], v[154:157]
	v_mfma_f32_16x16x32_bf16 v[142:145], v[110:113], v[192:195], v[142:145]
	v_mfma_f32_16x16x32_bf16 v[138:141], v[118:121], v[192:195], v[138:141]
	v_mfma_f32_16x16x32_bf16 v[94:97], v[110:113], v[200:203], v[94:97]
	v_mfma_f32_16x16x32_bf16 v[90:93], v[118:121], v[200:203], v[90:93]
	v_mfma_f32_16x16x32_bf16 v[78:81], v[110:113], v[208:211], v[78:81]
	v_mfma_f32_16x16x32_bf16 v[74:77], v[118:121], v[208:211], v[74:77]
	v_mfma_f32_16x16x32_bf16 v[150:153], v[122:125], v[162:165], v[150:153]
	v_mfma_f32_16x16x32_bf16 v[146:149], v[130:133], v[162:165], v[146:149]
	v_mfma_f32_16x16x32_bf16 v[102:105], v[122:125], v[170:173], v[102:105]
	v_mfma_f32_16x16x32_bf16 v[98:101], v[130:133], v[170:173], v[98:101]
	v_mfma_f32_16x16x32_bf16 v[86:89], v[122:125], v[196:199], v[86:89]
	v_mfma_f32_16x16x32_bf16 v[82:85], v[130:133], v[196:199], v[82:85]
	v_mfma_f32_16x16x32_bf16 v[70:73], v[122:125], v[204:207], v[70:73]
	v_mfma_f32_16x16x32_bf16 v[66:69], v[130:133], v[204:207], v[66:69]
	v_mfma_f32_16x16x32_bf16 v[150:153], v[126:129], v[166:169], v[150:153]
	v_mfma_f32_16x16x32_bf16 v[146:149], v[134:137], v[166:169], v[146:149]
	v_mfma_f32_16x16x32_bf16 v[102:105], v[126:129], v[192:195], v[102:105]
	v_mfma_f32_16x16x32_bf16 v[98:101], v[134:137], v[192:195], v[98:101]
	v_mfma_f32_16x16x32_bf16 v[86:89], v[126:129], v[200:203], v[86:89]
	v_mfma_f32_16x16x32_bf16 v[82:85], v[134:137], v[200:203], v[82:85]
	v_mfma_f32_16x16x32_bf16 v[70:73], v[126:129], v[208:211], v[70:73]
	v_mfma_f32_16x16x32_bf16 v[66:69], v[134:137], v[208:211], v[66:69]
	s_barrier
; #define PG8_STAGE(bufoff, gbase, voff) do { _Pragma("unroll") for (int _i = 0; _i < 2; ++_i) \
;         __builtin_amdgcn_global_load_lds((const unsigned*)((const char*)(gbase) + (voff)[_i]), (PG8_LAS unsigned*)(lds + (bufoff) + ldsw + _i * 8192), 16, 0, 0); } while (0)
; #define PG8_LDA(dst, b, h) do { _Pragma("unroll") for (int m = 0; m < 4; ++m) _Pragma("unroll") for (int k = 0; k < 2; ++k) dst[m][k] = *(const PG8_LAS bf16x8*)(lds + PG8_SA(b, h) + aoff + m * 2048 + k * 1024); } while (0)
; #define PG8_MMA(ai, bj, At, Bt) do { __builtin_amdgcn_s_setprio(1); _Pragma("unroll") for (int m = 0; m < 4; ++m) _Pragma("unroll") for (int n = 0; n < 2; ++n) _Pragma("unroll") for (int k = 0; k < 2; ++k) \
;         acc[ai][bj][m][n] = __builtin_amdgcn_mfma_f32_16x16x32_bf16(Bt[n][k], At[m][k], acc[ai][bj][m][n], 0, 0, 0); __builtin_amdgcn_s_setprio(0); } while (0)
; #define PG8_WAIT_V(n) asm volatile("s_waitcnt vmcnt(" #n ")" ::: "memory")
; #define PG8_WAIT_L(n) asm volatile("s_waitcnt lgkmcnt(" #n ")" ::: "memory")
; #define PG8_BAR __builtin_amdgcn_s_barrier()
; #define PG8_SCHED __builtin_amdgcn_sched_barrier(0)
; template <class Epi, class Sched, bool ALIGN_EPI = false, bool SP2 = false>
; __device__ __forceinline__ void gemm_phase(PG8_LAS unsigned char* lds, const Gemm g, const Sched& S, const Epi& E) {
;     ...
;             PG8_LDA(At, 1, 1); PG8_STAGE(PG8_SB(1, 0), b3, voffB); PG8_STAGE(PG8_SB(1, 1), b3 + hstep, voffB); PG8_STAGE(PG8_SA(1, 0), a3, voffA);
;             PG8_WAIT_V(8); PG8_WAIT_L(0); PG8_BAR; PG8_MMA(1, 0, At, B0); PG8_MMA(1, 1, At, B1); PG8_BAR; PG8_SCHED;
;     ...
;         if constexpr (ALIGN_EPI) { if (wr == 0) PG8_BAR; }
	s_add_i32 s46, s69, s52
	v_lshl_add_u64 v[212:213], v[212:213], 0, s[96:97]
	s_mov_b32 m0, s46
	ds_read_b128 v[162:165], v230 offset:49152
	ds_read_b128 v[166:169], v230 offset:50176
	ds_read_b128 v[170:173], v230 offset:51200
	ds_read_b128 v[192:195], v230 offset:52224
	ds_read_b128 v[196:199], v230 offset:53248
	ds_read_b128 v[200:203], v230 offset:54272
	ds_read_b128 v[204:207], v230 offset:55296
	ds_read_b128 v[208:211], v230 offset:56320
	global_load_lds_dwordx4 v[212:213], off
	s_add_i32 m0, s46, 0x2000
	s_add_u32 s44, s44, 0x40080
	v_lshl_add_u64 v[212:213], v[214:215], 0, s[96:97]
	s_addc_u32 s45, s45, 0
	s_add_i32 s46, s70, s52
	global_load_lds_dwordx4 v[212:213], off
	v_lshl_add_u64 v[212:213], s[44:45], 0, v[184:185]
	s_mov_b32 m0, s46
	s_nop 0
	global_load_lds_dwordx4 v[212:213], off
	v_lshl_add_u64 v[212:213], s[44:45], 0, v[180:181]
	s_add_i32 m0, s46, 0x2000
	s_nop 0
	global_load_lds_dwordx4 v[212:213], off
	v_lshl_add_u64 v[212:213], v[216:217], 0, s[96:97]
	s_mov_b32 m0, s60
	s_nop 0
	global_load_lds_dwordx4 v[212:213], off
	v_lshl_add_u64 v[212:213], v[218:219], 0, s[96:97]
	s_mov_b32 m0, s61
	s_nop 0
	global_load_lds_dwordx4 v[212:213], off
	s_waitcnt vmcnt(8)
	s_waitcnt lgkmcnt(0)
	s_barrier
	s_waitcnt lgkmcnt(0)
	v_mfma_f32_16x16x32_bf16 v[62:65], v[106:109], v[162:165], v[62:65]
	v_mfma_f32_16x16x32_bf16 v[58:61], v[114:117], v[162:165], v[58:61]
	v_mfma_f32_16x16x32_bf16 v[46:49], v[106:109], v[170:173], v[46:49]
	v_mfma_f32_16x16x32_bf16 v[42:45], v[114:117], v[170:173], v[42:45]
	v_mfma_f32_16x16x32_bf16 v[30:33], v[106:109], v[196:199], v[30:33]
	v_mfma_f32_16x16x32_bf16 v[26:29], v[114:117], v[196:199], v[26:29]
	v_mfma_f32_16x16x32_bf16 v[14:17], v[106:109], v[204:207], v[14:17]
	v_mfma_f32_16x16x32_bf16 v[10:13], v[114:117], v[204:207], v[10:13]
	v_mfma_f32_16x16x32_bf16 v[62:65], v[110:113], v[166:169], v[62:65]
	v_mfma_f32_16x16x32_bf16 v[58:61], v[118:121], v[166:169], v[58:61]
	v_mfma_f32_16x16x32_bf16 v[46:49], v[110:113], v[192:195], v[46:49]
	v_mfma_f32_16x16x32_bf16 v[42:45], v[118:121], v[192:195], v[42:45]
	v_mfma_f32_16x16x32_bf16 v[30:33], v[110:113], v[200:203], v[30:33]
	v_mfma_f32_16x16x32_bf16 v[26:29], v[118:121], v[200:203], v[26:29]
	v_mfma_f32_16x16x32_bf16 v[14:17], v[110:113], v[208:211], v[14:17]
	v_mfma_f32_16x16x32_bf16 v[10:13], v[118:121], v[208:211], v[10:13]
	v_mfma_f32_16x16x32_bf16 v[54:57], v[122:125], v[162:165], v[54:57]
	v_mfma_f32_16x16x32_bf16 v[50:53], v[130:133], v[162:165], v[50:53]
	v_mfma_f32_16x16x32_bf16 v[38:41], v[122:125], v[170:173], v[38:41]
	v_mfma_f32_16x16x32_bf16 v[34:37], v[130:133], v[170:173], v[34:37]
	v_mfma_f32_16x16x32_bf16 v[22:25], v[122:125], v[196:199], v[22:25]
	v_mfma_f32_16x16x32_bf16 v[18:21], v[130:133], v[196:199], v[18:21]
	v_mfma_f32_16x16x32_bf16 v[6:9], v[122:125], v[204:207], v[6:9]
	v_mfma_f32_16x16x32_bf16 v[2:5], v[130:133], v[204:207], v[2:5]
	v_mfma_f32_16x16x32_bf16 v[54:57], v[126:129], v[166:169], v[54:57]
	v_mfma_f32_16x16x32_bf16 v[50:53], v[134:137], v[166:169], v[50:53]
	v_mfma_f32_16x16x32_bf16 v[38:41], v[126:129], v[192:195], v[38:41]
	v_mfma_f32_16x16x32_bf16 v[34:37], v[134:137], v[192:195], v[34:37]
	v_mfma_f32_16x16x32_bf16 v[22:25], v[126:129], v[200:203], v[22:25]
	v_mfma_f32_16x16x32_bf16 v[18:21], v[134:137], v[200:203], v[18:21]
	v_mfma_f32_16x16x32_bf16 v[6:9], v[126:129], v[208:211], v[6:9]
	v_mfma_f32_16x16x32_bf16 v[2:5], v[134:137], v[208:211], v[2:5]
	s_barrier
	s_add_i32 s68, s68, 2
	s_add_u32 s8, s8, 0x100
	s_addc_u32 s9, s9, 0
	s_add_u32 s66, s66, 0x100
	s_addc_u32 s67, s67, 0
	s_cmp_gt_u32 s68, 13
	s_cbranch_scc0 .LBB0_1247
	s_setprio 0
	s_and_b64 vcc, exec, s[24:25]
	s_cbranch_vccz .LBB0_1250
	s_barrier

; template <class Epi, class Sched, bool ALIGN_EPI = false, bool SP2 = false>
; __device__ __forceinline__ void gemm_phase(PG8_LAS unsigned char* lds, const Gemm g, const Sched& S, const Epi& E) {
;     ...
;         for (int t = 0; t < nt; t += 2) {
;             const bool last = (t == nt - 2);
;             const char* a1 = cA + (size_t)(t + 1) * kstep;
;             const char* a2 = last ? nA : cA + (size_t)(t + 2) * kstep; const char* b2 = last ? nB : cB + (size_t)(t + 2) * kstep;
;             const char* a3 = a2 + kstep; const char* b3 = b2 + kstep;
.LBB0_1359:
	s_add_u32 s33, s24, 0x100
	s_addc_u32 s49, s25, 0
	s_mov_b32 s50, -2
	s_waitcnt lgkmcnt(0)
	s_cmp_eq_u64 s[14:15], 0
	s_cbranch_scc0 .Lmy_prio_1360
	s_setprio 1

; #define PG8_STAGE(bufoff, gbase, voff) do { _Pragma("unroll") for (int _i = 0; _i < 2; ++_i) \
;         __builtin_amdgcn_global_load_lds((const unsigned*)((const char*)(gbase) + (voff)[_i]), (PG8_LAS unsigned*)(lds + (bufoff) + ldsw + _i * 8192), 16, 0, 0); } while (0)
; #define PG8_LDA(dst, b, h) do { _Pragma("unroll") for (int m = 0; m < 4; ++m) _Pragma("unroll") for (int k = 0; k < 2; ++k) dst[m][k] = *(const PG8_LAS bf16x8*)(lds + PG8_SA(b, h) + aoff + m * 2048 + k * 1024); } while (0)
; #define PG8_MMA(ai, bj, At, Bt) do { __builtin_amdgcn_s_setprio(1); _Pragma("unroll") for (int m = 0; m < 4; ++m) _Pragma("unroll") for (int n = 0; n < 2; ++n) _Pragma("unroll") for (int k = 0; k < 2; ++k) \
;         acc[ai][bj][m][n] = __builtin_amdgcn_mfma_f32_16x16x32_bf16(Bt[n][k], At[m][k], acc[ai][bj][m][n], 0, 0, 0); __builtin_amdgcn_s_setprio(0); } while (0)
; #define PG8_WAIT_V(n) asm volatile("s_waitcnt vmcnt(" #n ")" ::: "memory")
; #define PG8_WAIT_L(n) asm volatile("s_waitcnt lgkmcnt(" #n ")" ::: "memory")
; #define PG8_BAR __builtin_amdgcn_s_barrier()
; #define PG8_SCHED __builtin_amdgcn_sched_barrier(0)
; template <class Epi, class Sched, bool ALIGN_EPI = false, bool SP2 = false>
; __device__ __forceinline__ void gemm_phase(PG8_LAS unsigned char* lds, const Gemm g, const Sched& S, const Epi& E) {
;     ...
;             PG8_WAIT_V(8); PG8_WAIT_L(0); PG8_BAR; PG8_MMA(0, 0, At, B0); PG8_MMA(0, 1, At, B1); PG8_BAR; PG8_SCHED;
;             PG8_LDA(At, 0, 1); PG8_STAGE(PG8_SB(0, 0), b2, voffB); PG8_STAGE(PG8_SB(0, 1), b2 + hstep, voffB); PG8_STAGE(PG8_SA(0, 0), a2, voffA);
;             PG8_WAIT_V(8); PG8_WAIT_L(0); PG8_BAR; PG8_MMA(1, 0, At, B0); PG8_MMA(1, 1, At, B1); PG8_BAR; PG8_SCHED;
.Lffout_noz:
	s_waitcnt vmcnt(8)
	s_waitcnt lgkmcnt(0)
	s_barrier
	s_waitcnt lgkmcnt(0)
	v_mfma_f32_16x16x32_bf16 v[142:145], v[114:117], v[180:183], v[142:145]
	v_mfma_f32_16x16x32_bf16 v[138:141], v[122:125], v[180:183], v[138:141]
	v_mfma_f32_16x16x32_bf16 v[110:113], v[114:117], v[192:195], v[110:113]
	v_mfma_f32_16x16x32_bf16 v[106:109], v[122:125], v[192:195], v[106:109]
	v_mfma_f32_16x16x32_bf16 v[94:97], v[114:117], v[200:203], v[94:97]
	v_mfma_f32_16x16x32_bf16 v[90:93], v[122:125], v[200:203], v[90:93]
	v_mfma_f32_16x16x32_bf16 v[78:81], v[114:117], v[208:211], v[78:81]
	v_mfma_f32_16x16x32_bf16 v[74:77], v[122:125], v[208:211], v[74:77]
	v_mfma_f32_16x16x32_bf16 v[142:145], v[118:121], v[188:191], v[142:145]
	v_mfma_f32_16x16x32_bf16 v[138:141], v[134:137], v[188:191], v[138:141]
	v_mfma_f32_16x16x32_bf16 v[110:113], v[118:121], v[196:199], v[110:113]
	v_mfma_f32_16x16x32_bf16 v[106:109], v[134:137], v[196:199], v[106:109]
	v_mfma_f32_16x16x32_bf16 v[94:97], v[118:121], v[204:207], v[94:97]
	v_mfma_f32_16x16x32_bf16 v[90:93], v[134:137], v[204:207], v[90:93]
	v_mfma_f32_16x16x32_bf16 v[78:81], v[118:121], v[212:215], v[78:81]
	v_mfma_f32_16x16x32_bf16 v[74:77], v[134:137], v[212:215], v[74:77]
	v_mfma_f32_16x16x32_bf16 v[130:133], v[146:149], v[180:183], v[130:133]
	v_mfma_f32_16x16x32_bf16 v[126:129], v[166:169], v[180:183], v[126:129]
	v_mfma_f32_16x16x32_bf16 v[102:105], v[146:149], v[192:195], v[102:105]
	v_mfma_f32_16x16x32_bf16 v[98:101], v[166:169], v[192:195], v[98:101]
	v_mfma_f32_16x16x32_bf16 v[86:89], v[146:149], v[200:203], v[86:89]
	v_mfma_f32_16x16x32_bf16 v[82:85], v[166:169], v[200:203], v[82:85]
	v_mfma_f32_16x16x32_bf16 v[70:73], v[146:149], v[208:211], v[70:73]
	v_mfma_f32_16x16x32_bf16 v[66:69], v[166:169], v[208:211], v[66:69]
	v_mfma_f32_16x16x32_bf16 v[130:133], v[150:153], v[188:191], v[130:133]
	v_mfma_f32_16x16x32_bf16 v[126:129], v[170:173], v[188:191], v[126:129]
	v_mfma_f32_16x16x32_bf16 v[102:105], v[150:153], v[196:199], v[102:105]
	v_mfma_f32_16x16x32_bf16 v[98:101], v[170:173], v[196:199], v[98:101]
	v_mfma_f32_16x16x32_bf16 v[86:89], v[150:153], v[204:207], v[86:89]
	v_mfma_f32_16x16x32_bf16 v[82:85], v[170:173], v[204:207], v[82:85]
	v_mfma_f32_16x16x32_bf16 v[70:73], v[150:153], v[212:215], v[70:73]
	v_mfma_f32_16x16x32_bf16 v[66:69], v[170:173], v[212:215], v[66:69]
	s_barrier
	s_add_i32 s22, s51, s34
	v_lshl_add_u64 v[216:217], s[24:25], 0, v[158:159]
	s_mov_b32 m0, s22
	ds_read_b128 v[180:183], v186 offset:16384
	ds_read_b128 v[188:191], v186 offset:17408
	ds_read_b128 v[192:195], v186 offset:18432
	ds_read_b128 v[196:199], v186 offset:19456
	ds_read_b128 v[200:203], v186 offset:20480
	ds_read_b128 v[204:207], v186 offset:21504
	ds_read_b128 v[208:211], v186 offset:22528
	ds_read_b128 v[212:215], v186 offset:23552
	global_load_lds_dwordx4 v[216:217], off
	s_add_i32 m0, s22, 0x2000
	s_add_u32 s22, s24, 0xb0000
	v_lshl_add_u64 v[218:219], s[24:25], 0, v[154:155]
	s_addc_u32 s23, s25, 0
	s_add_i32 s51, s52, s34
	global_load_lds_dwordx4 v[218:219], off
	v_lshl_add_u64 v[220:221], s[22:23], 0, v[158:159]
	s_mov_b32 m0, s51
	v_lshl_add_u64 v[222:223], s[26:27], 0, v[156:157]
	global_load_lds_dwordx4 v[220:221], off
	v_lshl_add_u64 v[220:221], s[22:23], 0, v[154:155]
	s_add_i32 m0, s51, 0x2000
	s_nop 0
	global_load_lds_dwordx4 v[220:221], off
	v_lshl_add_u64 v[220:221], s[26:27], 0, v[160:161]
	s_mov_b32 m0, s35
	s_nop 0
	global_load_lds_dwordx4 v[220:221], off
	s_mov_b32 m0, s36
	s_nop 0
	global_load_lds_dwordx4 v[222:223], off
	s_waitcnt vmcnt(8)
	s_waitcnt lgkmcnt(0)
	s_barrier
	s_waitcnt lgkmcnt(0)
	v_mfma_f32_16x16x32_bf16 v[62:65], v[114:117], v[180:183], v[62:65]
	v_mfma_f32_16x16x32_bf16 v[58:61], v[122:125], v[180:183], v[58:61]
	v_mfma_f32_16x16x32_bf16 v[46:49], v[114:117], v[192:195], v[46:49]
	v_mfma_f32_16x16x32_bf16 v[42:45], v[122:125], v[192:195], v[42:45]
	v_mfma_f32_16x16x32_bf16 v[30:33], v[114:117], v[200:203], v[30:33]
	v_mfma_f32_16x16x32_bf16 v[26:29], v[122:125], v[200:203], v[26:29]
	v_mfma_f32_16x16x32_bf16 v[14:17], v[114:117], v[208:211], v[14:17]
	v_mfma_f32_16x16x32_bf16 v[10:13], v[122:125], v[208:211], v[10:13]
	v_mfma_f32_16x16x32_bf16 v[62:65], v[118:121], v[188:191], v[62:65]
	v_mfma_f32_16x16x32_bf16 v[58:61], v[134:137], v[188:191], v[58:61]
	v_mfma_f32_16x16x32_bf16 v[46:49], v[118:121], v[196:199], v[46:49]
	v_mfma_f32_16x16x32_bf16 v[42:45], v[134:137], v[196:199], v[42:45]
	v_mfma_f32_16x16x32_bf16 v[30:33], v[118:121], v[204:207], v[30:33]
	v_mfma_f32_16x16x32_bf16 v[26:29], v[134:137], v[204:207], v[26:29]
	v_mfma_f32_16x16x32_bf16 v[14:17], v[118:121], v[212:215], v[14:17]
	v_mfma_f32_16x16x32_bf16 v[10:13], v[134:137], v[212:215], v[10:13]
	v_mfma_f32_16x16x32_bf16 v[54:57], v[146:149], v[180:183], v[54:57]
	v_mfma_f32_16x16x32_bf16 v[50:53], v[166:169], v[180:183], v[50:53]
	v_mfma_f32_16x16x32_bf16 v[38:41], v[146:149], v[192:195], v[38:41]
	v_mfma_f32_16x16x32_bf16 v[34:37], v[166:169], v[192:195], v[34:37]
	v_mfma_f32_16x16x32_bf16 v[22:25], v[146:149], v[200:203], v[22:25]
	v_mfma_f32_16x16x32_bf16 v[18:21], v[166:169], v[200:203], v[18:21]
	v_mfma_f32_16x16x32_bf16 v[6:9], v[146:149], v[208:211], v[6:9]
	v_mfma_f32_16x16x32_bf16 v[2:5], v[166:169], v[208:211], v[2:5]
	v_mfma_f32_16x16x32_bf16 v[54:57], v[150:153], v[188:191], v[54:57]
	v_mfma_f32_16x16x32_bf16 v[50:53], v[170:173], v[188:191], v[50:53]
	v_mfma_f32_16x16x32_bf16 v[38:41], v[150:153], v[196:199], v[38:41]
	v_mfma_f32_16x16x32_bf16 v[34:37], v[170:173], v[196:199], v[34:37]
	v_mfma_f32_16x16x32_bf16 v[22:25], v[150:153], v[204:207], v[22:25]
	v_mfma_f32_16x16x32_bf16 v[18:21], v[170:173], v[204:207], v[18:21]
	v_mfma_f32_16x16x32_bf16 v[6:9], v[150:153], v[212:215], v[6:9]
	v_mfma_f32_16x16x32_bf16 v[2:5], v[170:173], v[212:215], v[2:5]
	s_barrier
; #define PG8_STAGE(bufoff, gbase, voff) do { _Pragma("unroll") for (int _i = 0; _i < 2; ++_i) \
;         __builtin_amdgcn_global_load_lds((const unsigned*)((const char*)(gbase) + (voff)[_i]), (PG8_LAS unsigned*)(lds + (bufoff) + ldsw + _i * 8192), 16, 0, 0); } while (0)
; #define PG8_LDA(dst, b, h) do { _Pragma("unroll") for (int m = 0; m < 4; ++m) _Pragma("unroll") for (int k = 0; k < 2; ++k) dst[m][k] = *(const PG8_LAS bf16x8*)(lds + PG8_SA(b, h) + aoff + m * 2048 + k * 1024); } while (0)
; #define PG8_LDB(dst, b, h) do { _Pragma("unroll") for (int n = 0; n < 2; ++n) _Pragma("unroll") for (int k = 0; k < 2; ++k) dst[n][k] = *(const PG8_LAS bf16x8*)(lds + PG8_SB(b, h) + boff + n * 2048 + k * 1024); } while (0)
; #define PG8_MMA(ai, bj, At, Bt) do { __builtin_amdgcn_s_setprio(1); _Pragma("unroll") for (int m = 0; m < 4; ++m) _Pragma("unroll") for (int n = 0; n < 2; ++n) _Pragma("unroll") for (int k = 0; k < 2; ++k) \
;         acc[ai][bj][m][n] = __builtin_amdgcn_mfma_f32_16x16x32_bf16(Bt[n][k], At[m][k], acc[ai][bj][m][n], 0, 0, 0); __builtin_amdgcn_s_setprio(0); } while (0)
; #define PG8_WAIT_V(n) asm volatile("s_waitcnt vmcnt(" #n ")" ::: "memory")
; #define PG8_WAIT_L(n) asm volatile("s_waitcnt lgkmcnt(" #n ")" ::: "memory")
; #define PG8_BAR __builtin_amdgcn_s_barrier()
; #define PG8_SCHED __builtin_amdgcn_sched_barrier(0)
; template <class Epi, class Sched, bool ALIGN_EPI = false, bool SP2 = false>
; __device__ __forceinline__ void gemm_phase(PG8_LAS unsigned char* lds, const Gemm g, const Sched& S, const Epi& E) {
;     ...
;             PG8_LDB(B0, 1, 0); PG8_LDB(B1, 1, 1); PG8_SCHED; PG8_LDA(At, 1, 0); PG8_STAGE(PG8_SA(0, 1), a2 + hstep, voffA);
;             PG8_WAIT_V(8); PG8_WAIT_L(0); PG8_BAR; PG8_MMA(0, 0, At, B0); PG8_MMA(0, 1, At, B1); PG8_BAR; PG8_SCHED;
	s_add_i32 s51, 0, 0x18000
	s_add_i32 s52, 0, 0x1c000
	v_add_u32_e32 v134, s51, v185
	v_add_u32_e32 v170, s52, v185
	ds_read_b128 v[114:117], v134
	ds_read_b128 v[118:121], v134 offset:1024
	ds_read_b128 v[122:125], v134 offset:2048
	ds_read_b128 v[134:137], v134 offset:3072
	ds_read_b128 v[146:149], v170
	ds_read_b128 v[150:153], v170 offset:1024
	ds_read_b128 v[166:169], v170 offset:2048
	ds_read_b128 v[170:173], v170 offset:3072
	s_add_u32 s22, s26, 0xb0000
	s_addc_u32 s23, s27, 0
	s_mov_b32 m0, s37
	v_lshl_add_u64 v[228:229], s[22:23], 0, v[160:161]
	ds_read_b128 v[180:183], v186 offset:32768
	ds_read_b128 v[188:191], v186 offset:33792
	ds_read_b128 v[192:195], v186 offset:34816
	ds_read_b128 v[196:199], v186 offset:35840
	ds_read_b128 v[200:203], v186 offset:36864
	ds_read_b128 v[204:207], v186 offset:37888
	ds_read_b128 v[208:211], v186 offset:38912
	ds_read_b128 v[212:215], v186 offset:39936
	global_load_lds_dwordx4 v[228:229], off
	v_lshl_add_u64 v[228:229], s[22:23], 0, v[156:157]
	s_mov_b32 m0, s38
	s_nop 0
	global_load_lds_dwordx4 v[228:229], off
	s_waitcnt vmcnt(8)
	s_waitcnt lgkmcnt(0)
	s_barrier
	s_waitcnt lgkmcnt(0)
	v_mfma_f32_16x16x32_bf16 v[142:145], v[114:117], v[180:183], v[142:145]
	v_mfma_f32_16x16x32_bf16 v[138:141], v[122:125], v[180:183], v[138:141]
	v_mfma_f32_16x16x32_bf16 v[110:113], v[114:117], v[192:195], v[110:113]
	v_mfma_f32_16x16x32_bf16 v[106:109], v[122:125], v[192:195], v[106:109]
	v_mfma_f32_16x16x32_bf16 v[94:97], v[114:117], v[200:203], v[94:97]
	v_mfma_f32_16x16x32_bf16 v[90:93], v[122:125], v[200:203], v[90:93]
	v_mfma_f32_16x16x32_bf16 v[78:81], v[114:117], v[208:211], v[78:81]
	v_mfma_f32_16x16x32_bf16 v[74:77], v[122:125], v[208:211], v[74:77]
	v_mfma_f32_16x16x32_bf16 v[142:145], v[118:121], v[188:191], v[142:145]
	v_mfma_f32_16x16x32_bf16 v[138:141], v[134:137], v[188:191], v[138:141]
	v_mfma_f32_16x16x32_bf16 v[110:113], v[118:121], v[196:199], v[110:113]
	v_mfma_f32_16x16x32_bf16 v[106:109], v[134:137], v[196:199], v[106:109]
	v_mfma_f32_16x16x32_bf16 v[94:97], v[118:121], v[204:207], v[94:97]
	v_mfma_f32_16x16x32_bf16 v[90:93], v[134:137], v[204:207], v[90:93]
	v_mfma_f32_16x16x32_bf16 v[78:81], v[118:121], v[212:215], v[78:81]
	v_mfma_f32_16x16x32_bf16 v[74:77], v[134:137], v[212:215], v[74:77]
	v_mfma_f32_16x16x32_bf16 v[130:133], v[146:149], v[180:183], v[130:133]
	v_mfma_f32_16x16x32_bf16 v[126:129], v[166:169], v[180:183], v[126:129]
	v_mfma_f32_16x16x32_bf16 v[102:105], v[146:149], v[192:195], v[102:105]
	v_mfma_f32_16x16x32_bf16 v[98:101], v[166:169], v[192:195], v[98:101]
	v_mfma_f32_16x16x32_bf16 v[86:89], v[146:149], v[200:203], v[86:89]
	v_mfma_f32_16x16x32_bf16 v[82:85], v[166:169], v[200:203], v[82:85]
	v_mfma_f32_16x16x32_bf16 v[70:73], v[146:149], v[208:211], v[70:73]
	v_mfma_f32_16x16x32_bf16 v[66:69], v[166:169], v[208:211], v[66:69]
	v_mfma_f32_16x16x32_bf16 v[130:133], v[150:153], v[188:191], v[130:133]
	v_mfma_f32_16x16x32_bf16 v[126:129], v[170:173], v[188:191], v[126:129]
	v_mfma_f32_16x16x32_bf16 v[102:105], v[150:153], v[196:199], v[102:105]
	v_mfma_f32_16x16x32_bf16 v[98:101], v[170:173], v[196:199], v[98:101]
	v_mfma_f32_16x16x32_bf16 v[86:89], v[150:153], v[204:207], v[86:89]
	v_mfma_f32_16x16x32_bf16 v[82:85], v[170:173], v[204:207], v[82:85]
	v_mfma_f32_16x16x32_bf16 v[70:73], v[150:153], v[212:215], v[70:73]
	v_mfma_f32_16x16x32_bf16 v[66:69], v[170:173], v[212:215], v[66:69]
	s_barrier
; #define PG8_STAGE(bufoff, gbase, voff) do { _Pragma("unroll") for (int _i = 0; _i < 2; ++_i) \
;         __builtin_amdgcn_global_load_lds((const unsigned*)((const char*)(gbase) + (voff)[_i]), (PG8_LAS unsigned*)(lds + (bufoff) + ldsw + _i * 8192), 16, 0, 0); } while (0)
; #define PG8_LDA(dst, b, h) do { _Pragma("unroll") for (int m = 0; m < 4; ++m) _Pragma("unroll") for (int k = 0; k < 2; ++k) dst[m][k] = *(const PG8_LAS bf16x8*)(lds + PG8_SA(b, h) + aoff + m * 2048 + k * 1024); } while (0)
; #define PG8_MMA(ai, bj, At, Bt) do { __builtin_amdgcn_s_setprio(1); _Pragma("unroll") for (int m = 0; m < 4; ++m) _Pragma("unroll") for (int n = 0; n < 2; ++n) _Pragma("unroll") for (int k = 0; k < 2; ++k) \
;         acc[ai][bj][m][n] = __builtin_amdgcn_mfma_f32_16x16x32_bf16(Bt[n][k], At[m][k], acc[ai][bj][m][n], 0, 0, 0); __builtin_amdgcn_s_setprio(0); } while (0)
; #define PG8_WAIT_V(n) asm volatile("s_waitcnt vmcnt(" #n ")" ::: "memory")
; #define PG8_WAIT_L(n) asm volatile("s_waitcnt lgkmcnt(" #n ")" ::: "memory")
; #define PG8_BAR __builtin_amdgcn_s_barrier()
; #define PG8_SCHED __builtin_amdgcn_sched_barrier(0)
; template <class Epi, class Sched, bool ALIGN_EPI = false, bool SP2 = false>
; __device__ __forceinline__ void gemm_phase(PG8_LAS unsigned char* lds, const Gemm g, const Sched& S, const Epi& E) {
;     ...
;             PG8_LDA(At, 1, 1); PG8_STAGE(PG8_SB(1, 0), b3, voffB); PG8_STAGE(PG8_SB(1, 1), b3 + hstep, voffB); PG8_STAGE(PG8_SA(1, 0), a3, voffA);
;             PG8_WAIT_V(8); PG8_WAIT_L(0); PG8_BAR; PG8_MMA(1, 0, At, B0); PG8_MMA(1, 1, At, B1); PG8_BAR; PG8_SCHED;
;     ...
;         if constexpr (ALIGN_EPI) { if (wr == 0) PG8_BAR; }
	s_add_i32 s22, s51, s34
	v_lshl_add_u64 v[216:217], v[216:217], 0, s[96:97]
	s_mov_b32 m0, s22
	ds_read_b128 v[180:183], v186 offset:49152
	ds_read_b128 v[188:191], v186 offset:50176
	ds_read_b128 v[192:195], v186 offset:51200
	ds_read_b128 v[196:199], v186 offset:52224
	ds_read_b128 v[200:203], v186 offset:53248
	ds_read_b128 v[204:207], v186 offset:54272
	ds_read_b128 v[208:211], v186 offset:55296
	ds_read_b128 v[212:215], v186 offset:56320
	global_load_lds_dwordx4 v[216:217], off
	s_add_i32 m0, s22, 0x2000
	s_add_u32 s22, s24, 0xb0080
	v_lshl_add_u64 v[216:217], v[218:219], 0, s[96:97]
	s_addc_u32 s23, s25, 0
	s_add_i32 s24, s52, s34
	global_load_lds_dwordx4 v[216:217], off
	v_lshl_add_u64 v[216:217], s[22:23], 0, v[158:159]
	s_mov_b32 m0, s24
	s_nop 0
	global_load_lds_dwordx4 v[216:217], off
	v_lshl_add_u64 v[216:217], s[22:23], 0, v[154:155]
	s_add_i32 m0, s24, 0x2000
	s_nop 0
	global_load_lds_dwordx4 v[216:217], off
	v_lshl_add_u64 v[216:217], v[220:221], 0, s[96:97]
	s_mov_b32 m0, s41
	s_nop 0
	global_load_lds_dwordx4 v[216:217], off
	v_lshl_add_u64 v[216:217], v[222:223], 0, s[96:97]
	s_mov_b32 m0, s42
	s_nop 0
	global_load_lds_dwordx4 v[216:217], off
	s_waitcnt vmcnt(8)
	s_waitcnt lgkmcnt(0)
	s_barrier
	s_waitcnt lgkmcnt(0)
	v_mfma_f32_16x16x32_bf16 v[62:65], v[114:117], v[180:183], v[62:65]
	v_mfma_f32_16x16x32_bf16 v[58:61], v[122:125], v[180:183], v[58:61]
	v_mfma_f32_16x16x32_bf16 v[46:49], v[114:117], v[192:195], v[46:49]
	v_mfma_f32_16x16x32_bf16 v[42:45], v[122:125], v[192:195], v[42:45]
	v_mfma_f32_16x16x32_bf16 v[30:33], v[114:117], v[200:203], v[30:33]
	v_mfma_f32_16x16x32_bf16 v[26:29], v[122:125], v[200:203], v[26:29]
	v_mfma_f32_16x16x32_bf16 v[14:17], v[114:117], v[208:211], v[14:17]
	v_mfma_f32_16x16x32_bf16 v[10:13], v[122:125], v[208:211], v[10:13]
	v_mfma_f32_16x16x32_bf16 v[62:65], v[118:121], v[188:191], v[62:65]
	v_mfma_f32_16x16x32_bf16 v[58:61], v[134:137], v[188:191], v[58:61]
	v_mfma_f32_16x16x32_bf16 v[46:49], v[118:121], v[196:199], v[46:49]
	v_mfma_f32_16x16x32_bf16 v[42:45], v[134:137], v[196:199], v[42:45]
	v_mfma_f32_16x16x32_bf16 v[30:33], v[118:121], v[204:207], v[30:33]
	v_mfma_f32_16x16x32_bf16 v[26:29], v[134:137], v[204:207], v[26:29]
	v_mfma_f32_16x16x32_bf16 v[14:17], v[118:121], v[212:215], v[14:17]
	v_mfma_f32_16x16x32_bf16 v[10:13], v[134:137], v[212:215], v[10:13]
	v_mfma_f32_16x16x32_bf16 v[54:57], v[146:149], v[180:183], v[54:57]
	v_mfma_f32_16x16x32_bf16 v[50:53], v[166:169], v[180:183], v[50:53]
	v_mfma_f32_16x16x32_bf16 v[38:41], v[146:149], v[192:195], v[38:41]
	v_mfma_f32_16x16x32_bf16 v[34:37], v[166:169], v[192:195], v[34:37]
	v_mfma_f32_16x16x32_bf16 v[22:25], v[146:149], v[200:203], v[22:25]
	v_mfma_f32_16x16x32_bf16 v[18:21], v[166:169], v[200:203], v[18:21]
	v_mfma_f32_16x16x32_bf16 v[6:9], v[146:149], v[208:211], v[6:9]
	v_mfma_f32_16x16x32_bf16 v[2:5], v[166:169], v[208:211], v[2:5]
	v_mfma_f32_16x16x32_bf16 v[54:57], v[150:153], v[188:191], v[54:57]
	v_mfma_f32_16x16x32_bf16 v[50:53], v[170:173], v[188:191], v[50:53]
	v_mfma_f32_16x16x32_bf16 v[38:41], v[150:153], v[196:199], v[38:41]
	v_mfma_f32_16x16x32_bf16 v[34:37], v[170:173], v[196:199], v[34:37]
	v_mfma_f32_16x16x32_bf16 v[22:25], v[150:153], v[204:207], v[22:25]
	v_mfma_f32_16x16x32_bf16 v[18:21], v[170:173], v[204:207], v[18:21]
	v_mfma_f32_16x16x32_bf16 v[6:9], v[150:153], v[212:215], v[6:9]
	v_mfma_f32_16x16x32_bf16 v[2:5], v[170:173], v[212:215], v[2:5]
	s_barrier
	s_add_i32 s50, s50, 2
	s_add_u32 s33, s33, 0x100
	s_addc_u32 s49, s49, 0
	s_cmp_gt_u32 s50, 41
	s_mov_b64 s[22:23], s[8:9]
	s_cbranch_scc0 .LBB0_1360
	s_setprio 0
	s_and_b64 vcc, exec, s[14:15]
	s_cbranch_vccz .LBB0_1363
	s_barrier
